# differential-attention loop softmax stream: dependent VALU chains broken (rotating temps for the scale/exp pairs, two max accumulators, four partial row sums) + K/V LDS-DMA pieces use SGPR-base addres
# baseline (speedup 1.0000x reference)
.Lnl_be:
	s_barrier
	s_cmp_lt_i32 s96, s9
	s_cbranch_scc0 .Lnl_noVe
	s_cmp_lt_i32 s11, 1
	s_cbranch_scc1 .Lnl_noVe
	s_sub_u32 s6, s50, 0x60000
	s_subb_u32 s7, s51, 0
	s_add_i32 s12, s10, 0x10000
	s_and_b32 s12, s12, 0x18000
	s_add_i32 s12, s90, s12
	s_add_u32 s100, s78, s6
	s_addc_u32 s101, s79, s7
	s_mov_b32 m0, s12
	s_nop 0
	global_load_lds_dwordx4 v172, s[100:101]
	s_add_i32 m0, s12, 0x2000
	s_nop 0
	global_load_lds_dwordx4 v170, s[100:101]
.Lnl_noVe:
	s_add_i32 s97, s11, 3
	s_cmp_lt_i32 s97, s9
	s_cbranch_scc0 .Lnl_noKe
	s_add_i32 s12, s10, 0x18000
	s_and_b32 s12, s12, 0x18000
	s_add_i32 s12, s90, s12
	s_add_u32 s100, s78, s52
	s_addc_u32 s101, s79, s53
	s_add_i32 m0, s12, 0x4000
	s_nop 0
	global_load_lds_dwordx4 v168, s[100:101]
	s_add_i32 m0, s12, 0x6000
	s_nop 0
	global_load_lds_dwordx4 v166, s[100:101]
.Lnl_noKe:
	s_cmp_eq_u32 s11, 0
	s_cbranch_scc0 .Lnl_me
	v_max_f32_e32 v206, v81, v81
	v_max_f32_e32 v207, v80, v80
	v_max_f32_e32 v206, v207, v206
	v_max3_f32 v206, v206, v82, v83
	v_max3_f32 v174, v84, v85, v85
	v_max3_f32 v206, v206, v86, v87
	v_max3_f32 v174, v174, v88, v89
	v_max3_f32 v206, v206, v90, v91
	v_max3_f32 v174, v174, v92, v93
	v_max3_f32 v206, v206, v94, v95
	v_max3_f32 v174, v174, v96, v97
	v_max3_f32 v206, v206, v98, v99
	v_max3_f32 v174, v174, v100, v101
	v_max3_f32 v206, v206, v102, v103
	v_max3_f32 v174, v174, v104, v105
	v_max3_f32 v206, v206, v106, v107
	v_max3_f32 v174, v174, v108, v109
	v_max3_f32 v206, v206, v110, v111
	v_max_f32_e32 v206, v206, v174
	v_mov_b32_e32 v207, v206
	s_nop 1
	v_permlane32_swap_b32_e32 v206, v207
	v_max_f32_e32 v207, v207, v207
	v_max_f32_e32 v206, v206, v206
	v_max_f32_e32 v206, v206, v207
	s_add_i32 s6, s10, 0x8000
	s_and_b32 s6, s6, 0x18000
	v_add_u32_e32 v0, s6, v175
	ds_read_b128 v[2:5], v0 offset:0
	ds_read_b128 v[6:9], v0 offset:8192
	v_add_u32_e32 v0, s6, v176
	ds_read_b128 v[10:13], v0 offset:0
	ds_read_b128 v[160:163], v0 offset:8192
	v_sub_f32_e32 v207, v206, v193
	v_cmp_ge_f32_e64 s[0:1], s27, v207
	v_max_f32_e32 v206, v206, v206
	v_max_f32_e32 v207, v193, v193
	v_max_f32_e32 v206, v207, v206
	s_cmp_eq_u64 s[0:1], exec
	s_cselect_b64 s[0:1], -1, 0
	v_cndmask_b32_e64 v14, v206, v193, s[0:1]
	v_mul_f32_e32 v207, 0xbe38aa3b, v14
	v_fmamk_f32 v174, v80, 0x3e38aa3b, v207
	v_exp_f32_e32 v80, v174
	v_fmamk_f32 v208, v81, 0x3e38aa3b, v207
	v_exp_f32_e32 v81, v208
	v_fmamk_f32 v209, v82, 0x3e38aa3b, v207
	v_exp_f32_e32 v82, v209
	s_waitcnt lgkmcnt(0)
	v_mfma_f32_32x32x16_bf16 v[112:127], v[2:5], v[144:147], 0
	v_fmamk_f32 v174, v83, 0x3e38aa3b, v207
	v_exp_f32_e32 v83, v174
	v_fmamk_f32 v208, v84, 0x3e38aa3b, v207
	v_exp_f32_e32 v84, v208
	v_fmamk_f32 v209, v85, 0x3e38aa3b, v207
	v_exp_f32_e32 v85, v209
	v_fmamk_f32 v174, v86, 0x3e38aa3b, v207
	v_exp_f32_e32 v86, v174
	v_fmamk_f32 v208, v87, 0x3e38aa3b, v207
	v_exp_f32_e32 v87, v208
	v_fmamk_f32 v209, v88, 0x3e38aa3b, v207
	v_exp_f32_e32 v88, v209
	v_fmamk_f32 v174, v89, 0x3e38aa3b, v207
	v_exp_f32_e32 v89, v174
	v_add_u32_e32 v0, s6, v177
	ds_read_b128 v[2:5], v0 offset:0
	v_mfma_f32_32x32x16_bf16 v[128:143], v[6:9], v[144:147], 0
	ds_read_b128 v[6:9], v0 offset:8192
	v_fmamk_f32 v208, v90, 0x3e38aa3b, v207
	v_exp_f32_e32 v90, v208
	v_fmamk_f32 v209, v91, 0x3e38aa3b, v207
	v_exp_f32_e32 v91, v209
	v_fmamk_f32 v174, v92, 0x3e38aa3b, v207
	v_exp_f32_e32 v92, v174
	v_fmamk_f32 v208, v93, 0x3e38aa3b, v207
	v_exp_f32_e32 v93, v208
	v_fmamk_f32 v209, v94, 0x3e38aa3b, v207
	v_exp_f32_e32 v94, v209
	v_fmamk_f32 v174, v95, 0x3e38aa3b, v207
	v_exp_f32_e32 v95, v174
	v_fmamk_f32 v208, v96, 0x3e38aa3b, v207
	v_exp_f32_e32 v96, v208
	v_fmamk_f32 v209, v97, 0x3e38aa3b, v207
	v_add_u32_e32 v0, s6, v189
	v_mfma_f32_32x32x16_bf16 v[112:127], v[10:13], v[148:151], v[112:127]
	ds_read_b128 v[10:13], v0 offset:0
	ds_read_b128 v[182:185], v0 offset:8192
	v_exp_f32_e32 v97, v209
	v_fmamk_f32 v174, v98, 0x3e38aa3b, v207
	v_exp_f32_e32 v98, v174
	v_fmamk_f32 v208, v99, 0x3e38aa3b, v207
	v_exp_f32_e32 v99, v208
	v_fmamk_f32 v209, v100, 0x3e38aa3b, v207
	v_exp_f32_e32 v100, v209
	v_fmamk_f32 v174, v101, 0x3e38aa3b, v207
	v_exp_f32_e32 v101, v174
	v_fmamk_f32 v208, v102, 0x3e38aa3b, v207
	v_exp_f32_e32 v102, v208
	v_fmamk_f32 v209, v103, 0x3e38aa3b, v207
	v_exp_f32_e32 v103, v209
	v_fmamk_f32 v174, v104, 0x3e38aa3b, v207
	s_waitcnt lgkmcnt(0)
	v_mfma_f32_32x32x16_bf16 v[128:143], v[160:163], v[148:151], v[128:143]
	v_exp_f32_e32 v104, v174
	v_fmamk_f32 v208, v105, 0x3e38aa3b, v207
	v_exp_f32_e32 v105, v208
	v_fmamk_f32 v209, v106, 0x3e38aa3b, v207
	v_exp_f32_e32 v106, v209
	v_fmamk_f32 v174, v107, 0x3e38aa3b, v207
	v_exp_f32_e32 v107, v174
	v_fmamk_f32 v208, v108, 0x3e38aa3b, v207
	v_exp_f32_e32 v108, v208
	v_fmamk_f32 v209, v109, 0x3e38aa3b, v207
	v_exp_f32_e32 v109, v209
	v_fmamk_f32 v174, v110, 0x3e38aa3b, v207
	v_exp_f32_e32 v110, v174
	v_fmamk_f32 v208, v111, 0x3e38aa3b, v207
	v_mfma_f32_32x32x16_bf16 v[112:127], v[2:5], v[152:155], v[112:127]
	v_exp_f32_e32 v111, v208
	v_sub_f32_e32 v206, v193, v206
	v_mul_f32_e32 v206, 0x3e38aa3b, v206
	v_exp_f32_e32 v206, v206
	v_add_f32_e32 v207, 0, v80
	v_cndmask_b32_e64 v194, v206, 1.0, s[0:1]
	v_mov_b32_e32 v193, v14
	v_mov_b32_e32 v174, v81
	v_mov_b32_e32 v208, v82
	v_mov_b32_e32 v209, v83
	v_add_f32_e32 v207, v84, v207
	v_add_f32_e32 v174, v85, v174
	v_add_f32_e32 v208, v86, v208
	v_add_f32_e32 v209, v87, v209
	v_add_f32_e32 v207, v88, v207
	v_mfma_f32_32x32x16_bf16 v[128:143], v[6:9], v[152:155], v[128:143]
	v_add_f32_e32 v174, v89, v174
	v_add_f32_e32 v208, v90, v208
	v_add_f32_e32 v209, v91, v209
	v_add_f32_e32 v207, v92, v207
	v_add_f32_e32 v174, v93, v174
	v_add_f32_e32 v208, v94, v208
	v_add_f32_e32 v209, v95, v209
	v_add_f32_e32 v207, v96, v207
	v_add_f32_e32 v174, v97, v174
	v_add_f32_e32 v208, v98, v208
	v_add_f32_e32 v209, v99, v209
	v_add_f32_e32 v207, v100, v207
	v_add_f32_e32 v174, v101, v174
	v_add_f32_e32 v208, v102, v208
	v_mfma_f32_32x32x16_bf16 v[112:127], v[10:13], v[156:159], v[112:127]
	v_add_f32_e32 v209, v103, v209
	v_add_f32_e32 v207, v104, v207
	v_add_f32_e32 v174, v105, v174
	v_add_f32_e32 v208, v106, v208
	v_add_f32_e32 v209, v107, v209
	v_add_f32_e32 v207, v108, v207
	v_add_f32_e32 v174, v109, v174
	v_add_f32_e32 v208, v110, v208
	v_add_f32_e32 v207, v207, v174
	v_add_f32_e32 v208, v208, v209
	v_add_f32_e32 v207, v207, v208
	v_add_f32_e32 v15, v111, v207
	v_mov_b32_e32 v195, v15
	v_cvt_pk_bf16_f32 v80, v80, v81
	v_cvt_pk_bf16_f32 v81, v82, v83
	v_cvt_pk_bf16_f32 v82, v84, v85
	v_cvt_pk_bf16_f32 v83, v86, v87
	v_mfma_f32_32x32x16_bf16 v[128:143], v[182:185], v[156:159], v[128:143]
	v_cvt_pk_bf16_f32 v84, v88, v89
	v_cvt_pk_bf16_f32 v85, v90, v91
	v_cvt_pk_bf16_f32 v86, v92, v93
	v_cvt_pk_bf16_f32 v87, v94, v95
	v_cvt_pk_bf16_f32 v88, v96, v97
	v_cvt_pk_bf16_f32 v89, v98, v99
	v_cvt_pk_bf16_f32 v90, v100, v101
	v_cvt_pk_bf16_f32 v91, v102, v103
	v_cvt_pk_bf16_f32 v92, v104, v105
	v_cvt_pk_bf16_f32 v93, v106, v107
	v_cvt_pk_bf16_f32 v94, v108, v109
	v_cvt_pk_bf16_f32 v95, v110, v111
	s_nop 1
	v_permlane32_swap_b32_e32 v15, v195
	v_permlane32_swap_b32_e32 v80, v82
	v_permlane32_swap_b32_e32 v81, v83
	v_permlane32_swap_b32_e32 v84, v86
	v_permlane32_swap_b32_e32 v85, v87
	v_permlane32_swap_b32_e32 v88, v90
	v_permlane32_swap_b32_e32 v89, v91
	v_permlane32_swap_b32_e32 v92, v94
	v_permlane32_swap_b32_e32 v93, v95
	v_add_f32_e32 v15, v15, v195
	v_fmac_f32_e32 v15, v192, v194
	v_mov_b32_e32 v192, v15
	s_add_i32 s0, s10, 0x0
	s_and_b32 s0, s0, 0x18000
	v_add_u32_e32 v13, s0, v191
	ds_read_b64_tr_b16 v[96:97], v13 offset:0
	ds_read_b64_tr_b16 v[98:99], v13 offset:2048
	ds_read_b64_tr_b16 v[100:101], v13 offset:512
	ds_read_b64_tr_b16 v[102:103], v13 offset:2560
	ds_read_b64_tr_b16 v[104:105], v13 offset:1024
	ds_read_b64_tr_b16 v[106:107], v13 offset:3072
	ds_read_b64_tr_b16 v[108:109], v13 offset:1536
	ds_read_b64_tr_b16 v[110:111], v13 offset:3584
	v_mov_b32_e32 v194, 1.0
	s_branch .Lnl_qe

.Lnl_nors_ea:
	v_max_f32_e32 v206, v81, v81
	v_max_f32_e32 v207, v80, v80
	v_max_f32_e32 v206, v207, v206
	ds_read_b64_tr_b16 v[160:161], v13 offset:4096
	ds_read_b64_tr_b16 v[162:163], v13 offset:6144
	ds_read_b64_tr_b16 v[182:183], v13 offset:4608
	ds_read_b64_tr_b16 v[184:185], v13 offset:6656
	ds_read_b64_tr_b16 v[198:199], v13 offset:5120
	ds_read_b64_tr_b16 v[200:201], v13 offset:7168
	ds_read_b64_tr_b16 v[202:203], v13 offset:5632
	ds_read_b64_tr_b16 v[204:205], v13 offset:7680
	v_max3_f32 v206, v206, v82, v83
	v_max3_f32 v174, v84, v85, v85
	s_waitcnt lgkmcnt(8)
	v_max3_f32 v206, v206, v86, v87
	v_max3_f32 v174, v174, v88, v89
	v_max3_f32 v206, v206, v90, v91
	v_mfma_f32_32x32x16_bf16 v[64:79], v[128:131], v[112:115], v[64:79]
	v_max3_f32 v174, v174, v92, v93
	v_max3_f32 v206, v206, v94, v95
	v_max3_f32 v174, v174, v96, v97
	v_mfma_f32_32x32x16_bf16 v[48:63], v[132:135], v[112:115], v[48:63]
	v_max3_f32 v206, v206, v98, v99
	v_max3_f32 v174, v174, v100, v101
	v_mfma_f32_32x32x16_bf16 v[32:47], v[136:139], v[112:115], v[32:47]
	v_max3_f32 v206, v206, v102, v103
	v_max3_f32 v174, v174, v104, v105
	v_max3_f32 v206, v206, v106, v107
	v_mfma_f32_32x32x16_bf16 v[16:31], v[140:143], v[112:115], v[16:31]
	v_max3_f32 v174, v174, v108, v109
	v_max3_f32 v206, v206, v110, v111
	v_max_f32_e32 v206, v206, v174
	v_mov_b32_e32 v207, v206
	ds_read_b64_tr_b16 v[128:129], v13 offset:8192
	ds_read_b64_tr_b16 v[130:131], v13 offset:10240
	ds_read_b64_tr_b16 v[132:133], v13 offset:8704
	ds_read_b64_tr_b16 v[134:135], v13 offset:10752
	ds_read_b64_tr_b16 v[136:137], v13 offset:9216
	ds_read_b64_tr_b16 v[138:139], v13 offset:11264
	ds_read_b64_tr_b16 v[140:141], v13 offset:9728
	ds_read_b64_tr_b16 v[142:143], v13 offset:11776
	s_nop 1
	v_permlane32_swap_b32_e32 v206, v207
	s_waitcnt lgkmcnt(8)
	v_max_f32_e32 v207, v207, v207
	v_max_f32_e32 v206, v206, v206
	v_max_f32_e32 v206, v206, v207
	v_mfma_f32_32x32x16_bf16 v[64:79], v[160:163], v[116:119], v[64:79]
	v_sub_f32_e32 v207, v206, v193
	v_cmp_ge_f32_e64 s[0:1], s27, v207
	v_max_f32_e32 v206, v206, v206
	v_mfma_f32_32x32x16_bf16 v[48:63], v[182:185], v[116:119], v[48:63]
	v_max_f32_e32 v207, v193, v193
	v_max_f32_e32 v206, v207, v206
	v_mfma_f32_32x32x16_bf16 v[32:47], v[198:201], v[116:119], v[32:47]
	s_cmp_eq_u64 s[0:1], exec
	s_cselect_b64 s[0:1], -1, 0
	v_cndmask_b32_e64 v14, v206, v193, s[0:1]
	v_mul_f32_e32 v207, 0xbe38aa3b, v14
	v_mfma_f32_32x32x16_bf16 v[16:31], v[202:205], v[116:119], v[16:31]
	v_fmamk_f32 v174, v80, 0x3e38aa3b, v207
	v_exp_f32_e32 v80, v174
	v_fmamk_f32 v208, v81, 0x3e38aa3b, v207
	ds_read_b64_tr_b16 v[160:161], v13 offset:12288
	ds_read_b64_tr_b16 v[162:163], v13 offset:14336
	ds_read_b64_tr_b16 v[182:183], v13 offset:12800
	ds_read_b64_tr_b16 v[184:185], v13 offset:14848
	ds_read_b64_tr_b16 v[198:199], v13 offset:13312
	ds_read_b64_tr_b16 v[200:201], v13 offset:15360
	ds_read_b64_tr_b16 v[202:203], v13 offset:13824
	ds_read_b64_tr_b16 v[204:205], v13 offset:15872
	v_exp_f32_e32 v81, v208
	v_fmamk_f32 v209, v82, 0x3e38aa3b, v207
	s_waitcnt lgkmcnt(8)
	v_exp_f32_e32 v82, v209
	v_fmamk_f32 v174, v83, 0x3e38aa3b, v207
	v_exp_f32_e32 v83, v174
	v_mfma_f32_32x32x16_bf16 v[64:79], v[128:131], v[120:123], v[64:79]
	v_fmamk_f32 v208, v84, 0x3e38aa3b, v207
	v_exp_f32_e32 v84, v208
	v_fmamk_f32 v209, v85, 0x3e38aa3b, v207
	v_mfma_f32_32x32x16_bf16 v[48:63], v[132:135], v[120:123], v[48:63]
	v_exp_f32_e32 v85, v209
	v_fmamk_f32 v174, v86, 0x3e38aa3b, v207
	v_exp_f32_e32 v86, v174
	v_mfma_f32_32x32x16_bf16 v[32:47], v[136:139], v[120:123], v[32:47]
	v_fmamk_f32 v208, v87, 0x3e38aa3b, v207
	v_exp_f32_e32 v87, v208
	v_mfma_f32_32x32x16_bf16 v[16:31], v[140:143], v[120:123], v[16:31]
	v_fmamk_f32 v209, v88, 0x3e38aa3b, v207
	v_exp_f32_e32 v88, v209
	v_fmamk_f32 v174, v89, 0x3e38aa3b, v207
	s_waitcnt lgkmcnt(0)
	v_exp_f32_e32 v89, v174
	v_fmamk_f32 v208, v90, 0x3e38aa3b, v207
	v_exp_f32_e32 v90, v208
	v_mfma_f32_32x32x16_bf16 v[64:79], v[160:163], v[124:127], v[64:79]
	v_fmamk_f32 v209, v91, 0x3e38aa3b, v207
	v_exp_f32_e32 v91, v209
	v_mfma_f32_32x32x16_bf16 v[48:63], v[182:185], v[124:127], v[48:63]
	v_fmamk_f32 v174, v92, 0x3e38aa3b, v207
	v_exp_f32_e32 v92, v174
	v_fmamk_f32 v208, v93, 0x3e38aa3b, v207
	v_mfma_f32_32x32x16_bf16 v[32:47], v[198:201], v[124:127], v[32:47]
	v_exp_f32_e32 v93, v208
	v_fmamk_f32 v209, v94, 0x3e38aa3b, v207
	v_exp_f32_e32 v94, v209
	v_mfma_f32_32x32x16_bf16 v[16:31], v[202:205], v[124:127], v[16:31]
	v_fmamk_f32 v174, v95, 0x3e38aa3b, v207
	v_exp_f32_e32 v95, v174
	s_add_i32 s6, s10, 0x8000
	s_and_b32 s6, s6, 0x18000
	v_add_u32_e32 v0, s6, v175
	ds_read_b128 v[2:5], v0 offset:0
	ds_read_b128 v[6:9], v0 offset:8192
	v_add_u32_e32 v0, s6, v176
	ds_read_b128 v[10:13], v0 offset:0
	ds_read_b128 v[160:163], v0 offset:8192
	v_fmamk_f32 v208, v96, 0x3e38aa3b, v207
	v_exp_f32_e32 v96, v208
	v_fmamk_f32 v209, v97, 0x3e38aa3b, v207
	s_waitcnt lgkmcnt(0)
	v_mfma_f32_32x32x16_bf16 v[112:127], v[2:5], v[144:147], 0
	v_exp_f32_e32 v97, v209
	v_fmamk_f32 v174, v98, 0x3e38aa3b, v207
	v_exp_f32_e32 v98, v174
	v_add_u32_e32 v0, s6, v177
	ds_read_b128 v[2:5], v0 offset:0
	v_mfma_f32_32x32x16_bf16 v[128:143], v[6:9], v[144:147], 0
	ds_read_b128 v[6:9], v0 offset:8192
	v_fmamk_f32 v208, v99, 0x3e38aa3b, v207
	v_exp_f32_e32 v99, v208
	v_add_u32_e32 v0, s6, v189
	v_mfma_f32_32x32x16_bf16 v[112:127], v[10:13], v[148:151], v[112:127]
	ds_read_b128 v[10:13], v0 offset:0
	ds_read_b128 v[182:185], v0 offset:8192
	v_fmamk_f32 v209, v100, 0x3e38aa3b, v207
	v_exp_f32_e32 v100, v209
	v_fmamk_f32 v174, v101, 0x3e38aa3b, v207
	s_waitcnt lgkmcnt(0)
	v_mfma_f32_32x32x16_bf16 v[128:143], v[160:163], v[148:151], v[128:143]
	v_exp_f32_e32 v101, v174
	v_fmamk_f32 v208, v102, 0x3e38aa3b, v207
	v_exp_f32_e32 v102, v208
	v_mfma_f32_32x32x16_bf16 v[112:127], v[2:5], v[152:155], v[112:127]
	v_fmamk_f32 v209, v103, 0x3e38aa3b, v207
	v_exp_f32_e32 v103, v209
	v_mfma_f32_32x32x16_bf16 v[128:143], v[6:9], v[152:155], v[128:143]
	v_fmamk_f32 v174, v104, 0x3e38aa3b, v207
	v_exp_f32_e32 v104, v174
	v_fmamk_f32 v208, v105, 0x3e38aa3b, v207
	v_mfma_f32_32x32x16_bf16 v[112:127], v[10:13], v[156:159], v[112:127]
	v_exp_f32_e32 v105, v208
	v_fmamk_f32 v209, v106, 0x3e38aa3b, v207
	v_exp_f32_e32 v106, v209
	v_mfma_f32_32x32x16_bf16 v[128:143], v[182:185], v[156:159], v[128:143]
	v_fmamk_f32 v174, v107, 0x3e38aa3b, v207
	v_exp_f32_e32 v107, v174
	v_fmamk_f32 v208, v108, 0x3e38aa3b, v207
	v_exp_f32_e32 v108, v208
	v_fmamk_f32 v209, v109, 0x3e38aa3b, v207
	v_exp_f32_e32 v109, v209
	v_fmamk_f32 v174, v110, 0x3e38aa3b, v207
	v_exp_f32_e32 v110, v174
	v_fmamk_f32 v208, v111, 0x3e38aa3b, v207
	v_exp_f32_e32 v111, v208
	v_sub_f32_e32 v206, v193, v206
	v_mul_f32_e32 v206, 0x3e38aa3b, v206
	v_exp_f32_e32 v206, v206
	v_add_f32_e32 v207, 0, v80
	v_cndmask_b32_e64 v194, v206, 1.0, s[0:1]
	v_mov_b32_e32 v193, v14
	v_mov_b32_e32 v174, v81
	v_mov_b32_e32 v208, v82
	v_mov_b32_e32 v209, v83
	v_add_f32_e32 v207, v84, v207
	v_add_f32_e32 v174, v85, v174
	v_add_f32_e32 v208, v86, v208
	v_add_f32_e32 v209, v87, v209
	v_add_f32_e32 v207, v88, v207
	v_add_f32_e32 v174, v89, v174
	v_add_f32_e32 v208, v90, v208
	v_add_f32_e32 v209, v91, v209
	v_add_f32_e32 v207, v92, v207
	v_add_f32_e32 v174, v93, v174
	v_add_f32_e32 v208, v94, v208
	v_add_f32_e32 v209, v95, v209
	v_add_f32_e32 v207, v96, v207
	v_add_f32_e32 v174, v97, v174
	v_add_f32_e32 v208, v98, v208
	v_add_f32_e32 v209, v99, v209
	v_add_f32_e32 v207, v100, v207
	v_add_f32_e32 v174, v101, v174
	v_add_f32_e32 v208, v102, v208
	v_add_f32_e32 v209, v103, v209
	v_add_f32_e32 v207, v104, v207
	v_add_f32_e32 v174, v105, v174
	v_add_f32_e32 v208, v106, v208
	v_add_f32_e32 v209, v107, v209
	v_add_f32_e32 v207, v108, v207
	v_add_f32_e32 v174, v109, v174
	v_add_f32_e32 v208, v110, v208
	v_add_f32_e32 v207, v207, v174
	v_add_f32_e32 v208, v208, v209
	v_add_f32_e32 v207, v207, v208
	v_add_f32_e32 v15, v111, v207
	v_mov_b32_e32 v195, v15
	v_cvt_pk_bf16_f32 v80, v80, v81
	v_cvt_pk_bf16_f32 v81, v82, v83
	v_cvt_pk_bf16_f32 v82, v84, v85
	v_cvt_pk_bf16_f32 v83, v86, v87
	v_cvt_pk_bf16_f32 v84, v88, v89
	v_cvt_pk_bf16_f32 v85, v90, v91
	v_cvt_pk_bf16_f32 v86, v92, v93
	v_cvt_pk_bf16_f32 v87, v94, v95
	v_cvt_pk_bf16_f32 v88, v96, v97
	v_cvt_pk_bf16_f32 v89, v98, v99
	v_cvt_pk_bf16_f32 v90, v100, v101
	v_cvt_pk_bf16_f32 v91, v102, v103
	v_cvt_pk_bf16_f32 v92, v104, v105
	v_cvt_pk_bf16_f32 v93, v106, v107
	v_cvt_pk_bf16_f32 v94, v108, v109
	v_cvt_pk_bf16_f32 v95, v110, v111
	s_nop 1
	v_permlane32_swap_b32_e32 v15, v195
	v_permlane32_swap_b32_e32 v80, v82
	v_permlane32_swap_b32_e32 v81, v83
	v_permlane32_swap_b32_e32 v84, v86
	v_permlane32_swap_b32_e32 v85, v87
	v_permlane32_swap_b32_e32 v88, v90
	v_permlane32_swap_b32_e32 v89, v91
	v_permlane32_swap_b32_e32 v92, v94
	v_permlane32_swap_b32_e32 v93, v95
	v_add_f32_e32 v15, v15, v195
	v_fmac_f32_e32 v15, v192, v194
	v_mov_b32_e32 v192, v15
	s_add_i32 s0, s10, 0x0
	s_and_b32 s0, s0, 0x18000
	v_add_u32_e32 v13, s0, v191
	ds_read_b64_tr_b16 v[96:97], v13 offset:0
	ds_read_b64_tr_b16 v[98:99], v13 offset:2048
	ds_read_b64_tr_b16 v[100:101], v13 offset:512
	ds_read_b64_tr_b16 v[102:103], v13 offset:2560
	ds_read_b64_tr_b16 v[104:105], v13 offset:1024
	ds_read_b64_tr_b16 v[106:107], v13 offset:3072
	ds_read_b64_tr_b16 v[108:109], v13 offset:1536
	ds_read_b64_tr_b16 v[110:111], v13 offset:3584
	s_branch .Lnl_J_e

.Lnl_nors_eb:
	v_max_f32_e32 v206, v81, v81
	v_max_f32_e32 v207, v80, v80
	v_max_f32_e32 v206, v207, v206
	v_max3_f32 v206, v206, v82, v83
	v_max3_f32 v174, v84, v85, v85
	v_max3_f32 v206, v206, v86, v87
	v_max3_f32 v174, v174, v88, v89
	v_max3_f32 v206, v206, v90, v91
	v_max3_f32 v174, v174, v92, v93
	v_max3_f32 v206, v206, v94, v95
	v_max3_f32 v174, v174, v96, v97
	v_max3_f32 v206, v206, v98, v99
	v_max3_f32 v174, v174, v100, v101
	v_max3_f32 v206, v206, v102, v103
	v_max3_f32 v174, v174, v104, v105
	v_max3_f32 v206, v206, v106, v107
	v_max3_f32 v174, v174, v108, v109
	v_max3_f32 v206, v206, v110, v111
	v_max_f32_e32 v206, v206, v174
	v_mov_b32_e32 v207, v206
	s_nop 1
	v_permlane32_swap_b32_e32 v206, v207
	v_max_f32_e32 v207, v207, v207
	v_max_f32_e32 v206, v206, v206
	v_max_f32_e32 v206, v206, v207
	v_sub_f32_e32 v207, v206, v193
	v_cmp_ge_f32_e64 s[0:1], s27, v207
	v_max_f32_e32 v206, v206, v206
	v_max_f32_e32 v207, v193, v193
	v_max_f32_e32 v206, v207, v206
	s_cmp_eq_u64 s[0:1], exec
	s_cselect_b64 s[0:1], -1, 0
	v_cndmask_b32_e64 v14, v206, v193, s[0:1]
	v_mul_f32_e32 v207, 0xbe38aa3b, v14
	v_fmamk_f32 v174, v80, 0x3e38aa3b, v207
	v_exp_f32_e32 v80, v174
	v_fmamk_f32 v208, v81, 0x3e38aa3b, v207
	v_exp_f32_e32 v81, v208
	v_fmamk_f32 v209, v82, 0x3e38aa3b, v207
	v_exp_f32_e32 v82, v209
	v_fmamk_f32 v174, v83, 0x3e38aa3b, v207
	v_exp_f32_e32 v83, v174
	v_fmamk_f32 v208, v84, 0x3e38aa3b, v207
	v_exp_f32_e32 v84, v208
	v_fmamk_f32 v209, v85, 0x3e38aa3b, v207
	v_exp_f32_e32 v85, v209
	v_fmamk_f32 v174, v86, 0x3e38aa3b, v207
	v_exp_f32_e32 v86, v174
	v_fmamk_f32 v208, v87, 0x3e38aa3b, v207
	v_exp_f32_e32 v87, v208
	v_fmamk_f32 v209, v88, 0x3e38aa3b, v207
	v_exp_f32_e32 v88, v209
	v_fmamk_f32 v174, v89, 0x3e38aa3b, v207
	v_exp_f32_e32 v89, v174
	v_fmamk_f32 v208, v90, 0x3e38aa3b, v207
	v_exp_f32_e32 v90, v208
	v_fmamk_f32 v209, v91, 0x3e38aa3b, v207
	v_exp_f32_e32 v91, v209
	v_fmamk_f32 v174, v92, 0x3e38aa3b, v207
	v_exp_f32_e32 v92, v174
	v_fmamk_f32 v208, v93, 0x3e38aa3b, v207
	v_exp_f32_e32 v93, v208
	v_fmamk_f32 v209, v94, 0x3e38aa3b, v207
	v_exp_f32_e32 v94, v209
	v_fmamk_f32 v174, v95, 0x3e38aa3b, v207
	v_exp_f32_e32 v95, v174
	v_fmamk_f32 v208, v96, 0x3e38aa3b, v207
	v_exp_f32_e32 v96, v208
	v_fmamk_f32 v209, v97, 0x3e38aa3b, v207
	v_exp_f32_e32 v97, v209
	v_fmamk_f32 v174, v98, 0x3e38aa3b, v207
	v_exp_f32_e32 v98, v174
	v_fmamk_f32 v208, v99, 0x3e38aa3b, v207
	v_exp_f32_e32 v99, v208
	v_fmamk_f32 v209, v100, 0x3e38aa3b, v207
	ds_read_b64_tr_b16 v[160:161], v13 offset:4096
	ds_read_b64_tr_b16 v[162:163], v13 offset:6144
	ds_read_b64_tr_b16 v[182:183], v13 offset:4608
	ds_read_b64_tr_b16 v[184:185], v13 offset:6656
	ds_read_b64_tr_b16 v[198:199], v13 offset:5120
	ds_read_b64_tr_b16 v[200:201], v13 offset:7168
	ds_read_b64_tr_b16 v[202:203], v13 offset:5632
	ds_read_b64_tr_b16 v[204:205], v13 offset:7680
	v_exp_f32_e32 v100, v209
	v_fmamk_f32 v174, v101, 0x3e38aa3b, v207
	s_waitcnt lgkmcnt(8)
	v_exp_f32_e32 v101, v174
	v_fmamk_f32 v208, v102, 0x3e38aa3b, v207
	v_exp_f32_e32 v102, v208
	v_mfma_f32_32x32x16_bf16 v[64:79], v[128:131], v[112:115], v[64:79]
	v_fmamk_f32 v209, v103, 0x3e38aa3b, v207
	v_exp_f32_e32 v103, v209
	v_mfma_f32_32x32x16_bf16 v[48:63], v[132:135], v[112:115], v[48:63]
	v_fmamk_f32 v174, v104, 0x3e38aa3b, v207
	v_exp_f32_e32 v104, v174
	v_fmamk_f32 v208, v105, 0x3e38aa3b, v207
	v_mfma_f32_32x32x16_bf16 v[32:47], v[136:139], v[112:115], v[32:47]
	v_exp_f32_e32 v105, v208
	v_fmamk_f32 v209, v106, 0x3e38aa3b, v207
	v_mfma_f32_32x32x16_bf16 v[16:31], v[140:143], v[112:115], v[16:31]
	v_exp_f32_e32 v106, v209
	v_fmamk_f32 v174, v107, 0x3e38aa3b, v207
	v_exp_f32_e32 v107, v174
	ds_read_b64_tr_b16 v[128:129], v13 offset:8192
	ds_read_b64_tr_b16 v[130:131], v13 offset:10240
	ds_read_b64_tr_b16 v[132:133], v13 offset:8704
	ds_read_b64_tr_b16 v[134:135], v13 offset:10752
	ds_read_b64_tr_b16 v[136:137], v13 offset:9216
	ds_read_b64_tr_b16 v[138:139], v13 offset:11264
	ds_read_b64_tr_b16 v[140:141], v13 offset:9728
	ds_read_b64_tr_b16 v[142:143], v13 offset:11776
	v_fmamk_f32 v208, v108, 0x3e38aa3b, v207
	v_exp_f32_e32 v108, v208
	s_waitcnt lgkmcnt(8)
	v_fmamk_f32 v209, v109, 0x3e38aa3b, v207
	v_exp_f32_e32 v109, v209
	v_fmamk_f32 v174, v110, 0x3e38aa3b, v207
	v_mfma_f32_32x32x16_bf16 v[64:79], v[160:163], v[116:119], v[64:79]
	v_exp_f32_e32 v110, v174
	v_fmamk_f32 v208, v111, 0x3e38aa3b, v207
	v_exp_f32_e32 v111, v208
	v_mfma_f32_32x32x16_bf16 v[48:63], v[182:185], v[116:119], v[48:63]
	v_sub_f32_e32 v206, v193, v206
	v_mul_f32_e32 v206, 0x3e38aa3b, v206
	v_mfma_f32_32x32x16_bf16 v[32:47], v[198:201], v[116:119], v[32:47]
	v_exp_f32_e32 v206, v206
	v_add_f32_e32 v207, 0, v80
	v_cndmask_b32_e64 v194, v206, 1.0, s[0:1]
	v_mfma_f32_32x32x16_bf16 v[16:31], v[202:205], v[116:119], v[16:31]
	v_mov_b32_e32 v193, v14
	v_mov_b32_e32 v174, v81
	ds_read_b64_tr_b16 v[160:161], v13 offset:12288
	ds_read_b64_tr_b16 v[162:163], v13 offset:14336
	ds_read_b64_tr_b16 v[182:183], v13 offset:12800
	ds_read_b64_tr_b16 v[184:185], v13 offset:14848
	ds_read_b64_tr_b16 v[198:199], v13 offset:13312
	ds_read_b64_tr_b16 v[200:201], v13 offset:15360
	ds_read_b64_tr_b16 v[202:203], v13 offset:13824
	ds_read_b64_tr_b16 v[204:205], v13 offset:15872
	v_mov_b32_e32 v208, v82
	v_mov_b32_e32 v209, v83
	v_add_f32_e32 v207, v84, v207
	s_waitcnt lgkmcnt(8)
	v_add_f32_e32 v174, v85, v174
	v_add_f32_e32 v208, v86, v208
	v_mfma_f32_32x32x16_bf16 v[64:79], v[128:131], v[120:123], v[64:79]
	v_add_f32_e32 v209, v87, v209
	v_add_f32_e32 v207, v88, v207
	v_add_f32_e32 v174, v89, v174
	v_mfma_f32_32x32x16_bf16 v[48:63], v[132:135], v[120:123], v[48:63]
	v_add_f32_e32 v208, v90, v208
	v_add_f32_e32 v209, v91, v209
	v_add_f32_e32 v207, v92, v207
	v_mfma_f32_32x32x16_bf16 v[32:47], v[136:139], v[120:123], v[32:47]
	v_add_f32_e32 v174, v93, v174
	v_add_f32_e32 v208, v94, v208
	v_mfma_f32_32x32x16_bf16 v[16:31], v[140:143], v[120:123], v[16:31]
	v_add_f32_e32 v209, v95, v209
	v_add_f32_e32 v207, v96, v207
	v_add_f32_e32 v174, v97, v174
	s_waitcnt lgkmcnt(0)
	v_add_f32_e32 v208, v98, v208
	v_add_f32_e32 v209, v99, v209
	v_mfma_f32_32x32x16_bf16 v[64:79], v[160:163], v[124:127], v[64:79]
	v_add_f32_e32 v207, v100, v207
	v_add_f32_e32 v174, v101, v174
	v_add_f32_e32 v208, v102, v208
	v_mfma_f32_32x32x16_bf16 v[48:63], v[182:185], v[124:127], v[48:63]
	v_add_f32_e32 v209, v103, v209
	v_add_f32_e32 v207, v104, v207
	v_mfma_f32_32x32x16_bf16 v[32:47], v[198:201], v[124:127], v[32:47]
	v_add_f32_e32 v174, v105, v174
	v_add_f32_e32 v208, v106, v208
	v_add_f32_e32 v209, v107, v209
	v_mfma_f32_32x32x16_bf16 v[16:31], v[202:205], v[124:127], v[16:31]
	v_add_f32_e32 v207, v108, v207
	v_add_f32_e32 v174, v109, v174
	s_add_i32 s6, s10, 0x8000
	s_and_b32 s6, s6, 0x18000
	v_add_u32_e32 v0, s6, v175
	ds_read_b128 v[2:5], v0 offset:0
	ds_read_b128 v[6:9], v0 offset:8192
	v_add_u32_e32 v0, s6, v176
	ds_read_b128 v[10:13], v0 offset:0
	ds_read_b128 v[160:163], v0 offset:8192
	v_add_f32_e32 v208, v110, v208
	v_add_f32_e32 v207, v207, v174
	v_add_f32_e32 v208, v208, v209
	v_add_f32_e32 v207, v207, v208
	v_add_f32_e32 v15, v111, v207
	v_mov_b32_e32 v195, v15
	s_waitcnt lgkmcnt(0)
	v_mfma_f32_32x32x16_bf16 v[112:127], v[2:5], v[144:147], 0
	v_cvt_pk_bf16_f32 v80, v80, v81
	v_cvt_pk_bf16_f32 v81, v82, v83
	v_cvt_pk_bf16_f32 v82, v84, v85
	v_add_u32_e32 v0, s6, v177
	ds_read_b128 v[2:5], v0 offset:0
	v_mfma_f32_32x32x16_bf16 v[128:143], v[6:9], v[144:147], 0
	ds_read_b128 v[6:9], v0 offset:8192
	v_cvt_pk_bf16_f32 v83, v86, v87
	v_cvt_pk_bf16_f32 v84, v88, v89
	v_add_u32_e32 v0, s6, v189
	v_mfma_f32_32x32x16_bf16 v[112:127], v[10:13], v[148:151], v[112:127]
	ds_read_b128 v[10:13], v0 offset:0
	ds_read_b128 v[182:185], v0 offset:8192
	v_cvt_pk_bf16_f32 v85, v90, v91
	v_cvt_pk_bf16_f32 v86, v92, v93
	v_cvt_pk_bf16_f32 v87, v94, v95
	s_waitcnt lgkmcnt(0)
	v_mfma_f32_32x32x16_bf16 v[128:143], v[160:163], v[148:151], v[128:143]
	v_cvt_pk_bf16_f32 v88, v96, v97
	v_cvt_pk_bf16_f32 v89, v98, v99
	v_mfma_f32_32x32x16_bf16 v[112:127], v[2:5], v[152:155], v[112:127]
	v_cvt_pk_bf16_f32 v90, v100, v101
	v_cvt_pk_bf16_f32 v91, v102, v103
	v_cvt_pk_bf16_f32 v92, v104, v105
	v_mfma_f32_32x32x16_bf16 v[128:143], v[6:9], v[152:155], v[128:143]
	v_cvt_pk_bf16_f32 v93, v106, v107
	v_cvt_pk_bf16_f32 v94, v108, v109
	v_mfma_f32_32x32x16_bf16 v[112:127], v[10:13], v[156:159], v[112:127]
	v_cvt_pk_bf16_f32 v95, v110, v111
	s_nop 1
	v_permlane32_swap_b32_e32 v15, v195
	v_mfma_f32_32x32x16_bf16 v[128:143], v[182:185], v[156:159], v[128:143]
	v_permlane32_swap_b32_e32 v80, v82
	v_permlane32_swap_b32_e32 v81, v83
	v_permlane32_swap_b32_e32 v84, v86
	v_permlane32_swap_b32_e32 v85, v87
	v_permlane32_swap_b32_e32 v88, v90
	v_permlane32_swap_b32_e32 v89, v91
	v_permlane32_swap_b32_e32 v92, v94
	v_permlane32_swap_b32_e32 v93, v95
	v_add_f32_e32 v15, v15, v195
	v_fmac_f32_e32 v15, v192, v194
	v_mov_b32_e32 v192, v15
	s_add_i32 s0, s10, 0x0
	s_and_b32 s0, s0, 0x18000
	v_add_u32_e32 v13, s0, v191
	ds_read_b64_tr_b16 v[96:97], v13 offset:0
	ds_read_b64_tr_b16 v[98:99], v13 offset:2048
	ds_read_b64_tr_b16 v[100:101], v13 offset:512
	ds_read_b64_tr_b16 v[102:103], v13 offset:2560
	ds_read_b64_tr_b16 v[104:105], v13 offset:1024
	ds_read_b64_tr_b16 v[106:107], v13 offset:3072
	ds_read_b64_tr_b16 v[108:109], v13 offset:1536
	ds_read_b64_tr_b16 v[110:111], v13 offset:3584

.Lnl_bo:
	s_barrier
	s_cmp_lt_i32 s96, s9
	s_cbranch_scc0 .Lnl_noVo
	s_add_i32 s12, s10, 0x18000
	s_and_b32 s12, s12, 0x18000
	s_add_i32 s12, s90, s12
	s_add_u32 s100, s78, s50
	s_addc_u32 s101, s79, s51
	s_mov_b32 m0, s12
	s_nop 0
	global_load_lds_dwordx4 v172, s[100:101]
	s_add_i32 m0, s12, 0x2000
	s_nop 0
	global_load_lds_dwordx4 v170, s[100:101]
.Lnl_noVo:
	s_add_i32 s97, s11, 4
	s_cmp_lt_i32 s97, s9
	s_cbranch_scc0 .Lnl_noKo
	s_add_i32 s12, s10, 0x0
	s_and_b32 s12, s12, 0x18000
	s_add_i32 s12, s90, s12
	s_add_u32 s100, s78, s56
	s_addc_u32 s101, s79, s57
	s_add_i32 m0, s12, 0x4000
	s_nop 0
	global_load_lds_dwordx4 v168, s[100:101]
	s_add_i32 m0, s12, 0x6000
	s_nop 0
	global_load_lds_dwordx4 v166, s[100:101]

.Lnl_nors_ola:
	v_max_f32_e32 v206, v113, v113
	v_max_f32_e32 v207, v112, v112
	v_max_f32_e32 v206, v207, v206
	ds_read_b64_tr_b16 v[160:161], v13 offset:4096
	ds_read_b64_tr_b16 v[162:163], v13 offset:6144
	ds_read_b64_tr_b16 v[182:183], v13 offset:4608
	ds_read_b64_tr_b16 v[184:185], v13 offset:6656
	ds_read_b64_tr_b16 v[198:199], v13 offset:5120
	ds_read_b64_tr_b16 v[200:201], v13 offset:7168
	ds_read_b64_tr_b16 v[202:203], v13 offset:5632
	ds_read_b64_tr_b16 v[204:205], v13 offset:7680
	v_max3_f32 v206, v206, v114, v115
	v_max3_f32 v174, v116, v117, v117
	v_max3_f32 v206, v206, v118, v119
	s_waitcnt lgkmcnt(8)
	v_max3_f32 v174, v174, v120, v121
	v_max3_f32 v206, v206, v122, v123
	v_max3_f32 v174, v174, v124, v125
	v_max3_f32 v206, v206, v126, v127
	v_mfma_f32_32x32x16_bf16 v[64:79], v[96:99], v[80:83], v[64:79]
	v_max3_f32 v174, v174, v128, v129
	v_max3_f32 v206, v206, v130, v131
	v_max3_f32 v174, v174, v132, v133
	v_max3_f32 v206, v206, v134, v135
	v_mfma_f32_32x32x16_bf16 v[48:63], v[100:103], v[80:83], v[48:63]
	v_max3_f32 v174, v174, v136, v137
	v_max3_f32 v206, v206, v138, v139
	v_max3_f32 v174, v174, v140, v141
	v_mfma_f32_32x32x16_bf16 v[32:47], v[104:107], v[80:83], v[32:47]
	v_max3_f32 v206, v206, v142, v143
	v_max_f32_e32 v206, v206, v174
	v_mov_b32_e32 v207, v206
	s_nop 1
	v_permlane32_swap_b32_e32 v206, v207
	v_mfma_f32_32x32x16_bf16 v[16:31], v[108:111], v[80:83], v[16:31]
	v_max_f32_e32 v207, v207, v207
	v_max_f32_e32 v206, v206, v206
	v_max_f32_e32 v206, v206, v207
	v_sub_f32_e32 v207, v206, v193
	ds_read_b64_tr_b16 v[96:97], v13 offset:8192
	ds_read_b64_tr_b16 v[98:99], v13 offset:10240
	ds_read_b64_tr_b16 v[100:101], v13 offset:8704
	ds_read_b64_tr_b16 v[102:103], v13 offset:10752
	ds_read_b64_tr_b16 v[104:105], v13 offset:9216
	ds_read_b64_tr_b16 v[106:107], v13 offset:11264
	ds_read_b64_tr_b16 v[108:109], v13 offset:9728
	ds_read_b64_tr_b16 v[110:111], v13 offset:11776
	v_cmp_ge_f32_e64 s[0:1], s27, v207
	v_max_f32_e32 v206, v206, v206
	v_max_f32_e32 v207, v193, v193
	v_max_f32_e32 v206, v207, v206
	s_waitcnt lgkmcnt(8)
	s_cmp_eq_u64 s[0:1], exec
	s_cselect_b64 s[0:1], -1, 0
	v_cndmask_b32_e64 v14, v206, v193, s[0:1]
	v_mul_f32_e32 v207, 0xbe38aa3b, v14
	v_mfma_f32_32x32x16_bf16 v[64:79], v[160:163], v[84:87], v[64:79]
	v_fmamk_f32 v174, v112, 0x3e38aa3b, v207
	v_exp_f32_e32 v112, v174
	v_fmamk_f32 v208, v113, 0x3e38aa3b, v207
	v_exp_f32_e32 v113, v208
	v_mfma_f32_32x32x16_bf16 v[48:63], v[182:185], v[84:87], v[48:63]
	v_fmamk_f32 v209, v114, 0x3e38aa3b, v207
	v_exp_f32_e32 v114, v209
	v_fmamk_f32 v174, v115, 0x3e38aa3b, v207
	v_exp_f32_e32 v115, v174
	v_mfma_f32_32x32x16_bf16 v[32:47], v[198:201], v[84:87], v[32:47]
	v_fmamk_f32 v208, v116, 0x3e38aa3b, v207
	v_exp_f32_e32 v116, v208
	v_fmamk_f32 v209, v117, 0x3e38aa3b, v207
	v_exp_f32_e32 v117, v209
	v_mfma_f32_32x32x16_bf16 v[16:31], v[202:205], v[84:87], v[16:31]
	v_fmamk_f32 v174, v118, 0x3e38aa3b, v207
	v_exp_f32_e32 v118, v174
	v_fmamk_f32 v208, v119, 0x3e38aa3b, v207
	ds_read_b64_tr_b16 v[160:161], v13 offset:12288
	ds_read_b64_tr_b16 v[162:163], v13 offset:14336
	ds_read_b64_tr_b16 v[182:183], v13 offset:12800
	ds_read_b64_tr_b16 v[184:185], v13 offset:14848
	ds_read_b64_tr_b16 v[198:199], v13 offset:13312
	ds_read_b64_tr_b16 v[200:201], v13 offset:15360
	ds_read_b64_tr_b16 v[202:203], v13 offset:13824
	ds_read_b64_tr_b16 v[204:205], v13 offset:15872
	v_exp_f32_e32 v119, v208
	v_fmamk_f32 v209, v120, 0x3e38aa3b, v207
	v_exp_f32_e32 v120, v209
	v_fmamk_f32 v174, v121, 0x3e38aa3b, v207
	s_waitcnt lgkmcnt(8)
	v_exp_f32_e32 v121, v174
	v_fmamk_f32 v208, v122, 0x3e38aa3b, v207
	v_exp_f32_e32 v122, v208
	v_fmamk_f32 v209, v123, 0x3e38aa3b, v207
	v_mfma_f32_32x32x16_bf16 v[64:79], v[96:99], v[88:91], v[64:79]
	v_exp_f32_e32 v123, v209
	v_fmamk_f32 v174, v124, 0x3e38aa3b, v207
	v_exp_f32_e32 v124, v174
	v_fmamk_f32 v208, v125, 0x3e38aa3b, v207
	v_mfma_f32_32x32x16_bf16 v[48:63], v[100:103], v[88:91], v[48:63]
	v_exp_f32_e32 v125, v208
	v_fmamk_f32 v209, v126, 0x3e38aa3b, v207
	v_exp_f32_e32 v126, v209
	v_mfma_f32_32x32x16_bf16 v[32:47], v[104:107], v[88:91], v[32:47]
	v_fmamk_f32 v174, v127, 0x3e38aa3b, v207
	v_exp_f32_e32 v127, v174
	v_fmamk_f32 v208, v128, 0x3e38aa3b, v207
	v_exp_f32_e32 v128, v208
	v_mfma_f32_32x32x16_bf16 v[16:31], v[108:111], v[88:91], v[16:31]
	v_fmamk_f32 v209, v129, 0x3e38aa3b, v207
	v_exp_f32_e32 v129, v209
	v_fmamk_f32 v174, v130, 0x3e38aa3b, v207
	v_exp_f32_e32 v130, v174
	s_waitcnt lgkmcnt(0)
	v_fmamk_f32 v208, v131, 0x3e38aa3b, v207
	v_exp_f32_e32 v131, v208
	v_fmamk_f32 v209, v132, 0x3e38aa3b, v207
	v_exp_f32_e32 v132, v209
	v_mfma_f32_32x32x16_bf16 v[64:79], v[160:163], v[92:95], v[64:79]
	v_fmamk_f32 v174, v133, 0x3e38aa3b, v207
	v_exp_f32_e32 v133, v174
	v_fmamk_f32 v208, v134, 0x3e38aa3b, v207
	v_mfma_f32_32x32x16_bf16 v[48:63], v[182:185], v[92:95], v[48:63]
	v_exp_f32_e32 v134, v208
	v_fmamk_f32 v209, v135, 0x3e38aa3b, v207
	v_exp_f32_e32 v135, v209
	v_fmamk_f32 v174, v136, 0x3e38aa3b, v207
	v_mfma_f32_32x32x16_bf16 v[32:47], v[198:201], v[92:95], v[32:47]
	v_exp_f32_e32 v136, v174
	v_fmamk_f32 v208, v137, 0x3e38aa3b, v207
	v_exp_f32_e32 v137, v208
	v_fmamk_f32 v209, v138, 0x3e38aa3b, v207
	v_mfma_f32_32x32x16_bf16 v[16:31], v[202:205], v[92:95], v[16:31]
	v_exp_f32_e32 v138, v209
	v_fmamk_f32 v174, v139, 0x3e38aa3b, v207
	v_exp_f32_e32 v139, v174
	v_fmamk_f32 v208, v140, 0x3e38aa3b, v207
	v_exp_f32_e32 v140, v208
	v_fmamk_f32 v209, v141, 0x3e38aa3b, v207
	v_exp_f32_e32 v141, v209
	v_fmamk_f32 v174, v142, 0x3e38aa3b, v207
	v_exp_f32_e32 v142, v174
	v_fmamk_f32 v208, v143, 0x3e38aa3b, v207
	v_exp_f32_e32 v143, v208
	v_sub_f32_e32 v206, v193, v206
	v_mul_f32_e32 v206, 0x3e38aa3b, v206
	v_exp_f32_e32 v206, v206
	v_add_f32_e32 v207, 0, v112
	v_cndmask_b32_e64 v194, v206, 1.0, s[0:1]
	v_mov_b32_e32 v193, v14
	v_mov_b32_e32 v174, v113
	v_mov_b32_e32 v208, v114
	v_mov_b32_e32 v209, v115
	v_add_f32_e32 v207, v116, v207
	v_add_f32_e32 v174, v117, v174
	v_add_f32_e32 v208, v118, v208
	v_add_f32_e32 v209, v119, v209
	v_add_f32_e32 v207, v120, v207
	v_add_f32_e32 v174, v121, v174
	v_add_f32_e32 v208, v122, v208
	v_add_f32_e32 v209, v123, v209
	v_add_f32_e32 v207, v124, v207
	v_add_f32_e32 v174, v125, v174
	v_add_f32_e32 v208, v126, v208
	v_add_f32_e32 v209, v127, v209
	v_add_f32_e32 v207, v128, v207
	v_add_f32_e32 v174, v129, v174
	v_add_f32_e32 v208, v130, v208
	v_add_f32_e32 v209, v131, v209
	v_add_f32_e32 v207, v132, v207
	v_add_f32_e32 v174, v133, v174
	v_add_f32_e32 v208, v134, v208
	v_add_f32_e32 v209, v135, v209
	v_add_f32_e32 v207, v136, v207
	v_add_f32_e32 v174, v137, v174
	v_add_f32_e32 v208, v138, v208
	v_add_f32_e32 v209, v139, v209
	v_add_f32_e32 v207, v140, v207
	v_add_f32_e32 v174, v141, v174
	v_add_f32_e32 v208, v142, v208
	v_add_f32_e32 v207, v207, v174
	v_add_f32_e32 v208, v208, v209
	v_add_f32_e32 v207, v207, v208
	v_add_f32_e32 v15, v143, v207
	v_mov_b32_e32 v195, v15
	v_cvt_pk_bf16_f32 v112, v112, v113
	v_cvt_pk_bf16_f32 v113, v114, v115
	v_cvt_pk_bf16_f32 v114, v116, v117
	v_cvt_pk_bf16_f32 v115, v118, v119
	v_cvt_pk_bf16_f32 v116, v120, v121
	v_cvt_pk_bf16_f32 v117, v122, v123
	v_cvt_pk_bf16_f32 v118, v124, v125
	v_cvt_pk_bf16_f32 v119, v126, v127
	v_cvt_pk_bf16_f32 v120, v128, v129
	v_cvt_pk_bf16_f32 v121, v130, v131
	v_cvt_pk_bf16_f32 v122, v132, v133
	v_cvt_pk_bf16_f32 v123, v134, v135
	v_cvt_pk_bf16_f32 v124, v136, v137
	v_cvt_pk_bf16_f32 v125, v138, v139
	v_cvt_pk_bf16_f32 v126, v140, v141
	v_cvt_pk_bf16_f32 v127, v142, v143
	s_nop 1
	v_permlane32_swap_b32_e32 v15, v195
	v_permlane32_swap_b32_e32 v112, v114
	v_permlane32_swap_b32_e32 v113, v115
	v_permlane32_swap_b32_e32 v116, v118
	v_permlane32_swap_b32_e32 v117, v119
	v_permlane32_swap_b32_e32 v120, v122
	v_permlane32_swap_b32_e32 v121, v123
	v_permlane32_swap_b32_e32 v124, v126
	v_permlane32_swap_b32_e32 v125, v127
	v_add_f32_e32 v15, v15, v195
	v_fmac_f32_e32 v15, v192, v194
	v_mov_b32_e32 v192, v15
	s_add_i32 s0, s10, 0x8000
	s_and_b32 s0, s0, 0x18000
	v_add_u32_e32 v13, s0, v191
	ds_read_b64_tr_b16 v[128:129], v13 offset:0
	ds_read_b64_tr_b16 v[130:131], v13 offset:2048
	ds_read_b64_tr_b16 v[132:133], v13 offset:512
	ds_read_b64_tr_b16 v[134:135], v13 offset:2560
	ds_read_b64_tr_b16 v[136:137], v13 offset:1024
	ds_read_b64_tr_b16 v[138:139], v13 offset:3072
	ds_read_b64_tr_b16 v[140:141], v13 offset:1536
	ds_read_b64_tr_b16 v[142:143], v13 offset:3584
	s_branch .Lnl_J_ol

.Lnl_nors_olb:
	v_max_f32_e32 v206, v113, v113
	v_max_f32_e32 v207, v112, v112
	v_max_f32_e32 v206, v207, v206
	v_max3_f32 v206, v206, v114, v115
	v_max3_f32 v174, v116, v117, v117
	v_max3_f32 v206, v206, v118, v119
	v_max3_f32 v174, v174, v120, v121
	v_max3_f32 v206, v206, v122, v123
	v_max3_f32 v174, v174, v124, v125
	v_max3_f32 v206, v206, v126, v127
	v_max3_f32 v174, v174, v128, v129
	v_max3_f32 v206, v206, v130, v131
	v_max3_f32 v174, v174, v132, v133
	v_max3_f32 v206, v206, v134, v135
	v_max3_f32 v174, v174, v136, v137
	v_max3_f32 v206, v206, v138, v139
	v_max3_f32 v174, v174, v140, v141
	v_max3_f32 v206, v206, v142, v143
	v_max_f32_e32 v206, v206, v174
	v_mov_b32_e32 v207, v206
	s_nop 1
	v_permlane32_swap_b32_e32 v206, v207
	v_max_f32_e32 v207, v207, v207
	v_max_f32_e32 v206, v206, v206
	v_max_f32_e32 v206, v206, v207
	v_sub_f32_e32 v207, v206, v193
	v_cmp_ge_f32_e64 s[0:1], s27, v207
	v_max_f32_e32 v206, v206, v206
	v_max_f32_e32 v207, v193, v193
	v_max_f32_e32 v206, v207, v206
	s_cmp_eq_u64 s[0:1], exec
	s_cselect_b64 s[0:1], -1, 0
	v_cndmask_b32_e64 v14, v206, v193, s[0:1]
	v_mul_f32_e32 v207, 0xbe38aa3b, v14
	v_fmamk_f32 v174, v112, 0x3e38aa3b, v207
	v_exp_f32_e32 v112, v174
	v_fmamk_f32 v208, v113, 0x3e38aa3b, v207
	v_exp_f32_e32 v113, v208
	v_fmamk_f32 v209, v114, 0x3e38aa3b, v207
	v_exp_f32_e32 v114, v209
	v_fmamk_f32 v174, v115, 0x3e38aa3b, v207
	v_exp_f32_e32 v115, v174
	v_fmamk_f32 v208, v116, 0x3e38aa3b, v207
	v_exp_f32_e32 v116, v208
	v_fmamk_f32 v209, v117, 0x3e38aa3b, v207
	v_exp_f32_e32 v117, v209
	v_fmamk_f32 v174, v118, 0x3e38aa3b, v207
	v_exp_f32_e32 v118, v174
	v_fmamk_f32 v208, v119, 0x3e38aa3b, v207
	v_exp_f32_e32 v119, v208
	v_fmamk_f32 v209, v120, 0x3e38aa3b, v207
	v_exp_f32_e32 v120, v209
	v_fmamk_f32 v174, v121, 0x3e38aa3b, v207
	v_exp_f32_e32 v121, v174
	v_fmamk_f32 v208, v122, 0x3e38aa3b, v207
	v_exp_f32_e32 v122, v208
	v_fmamk_f32 v209, v123, 0x3e38aa3b, v207
	v_exp_f32_e32 v123, v209
	v_fmamk_f32 v174, v124, 0x3e38aa3b, v207
	v_exp_f32_e32 v124, v174
	v_fmamk_f32 v208, v125, 0x3e38aa3b, v207
	v_exp_f32_e32 v125, v208
	v_fmamk_f32 v209, v126, 0x3e38aa3b, v207
	v_exp_f32_e32 v126, v209
	v_fmamk_f32 v174, v127, 0x3e38aa3b, v207
	v_exp_f32_e32 v127, v174
	v_fmamk_f32 v208, v128, 0x3e38aa3b, v207
	v_exp_f32_e32 v128, v208
	v_fmamk_f32 v209, v129, 0x3e38aa3b, v207
	v_exp_f32_e32 v129, v209
	v_fmamk_f32 v174, v130, 0x3e38aa3b, v207
	v_exp_f32_e32 v130, v174
	v_fmamk_f32 v208, v131, 0x3e38aa3b, v207
	v_exp_f32_e32 v131, v208
	v_fmamk_f32 v209, v132, 0x3e38aa3b, v207
	ds_read_b64_tr_b16 v[160:161], v13 offset:4096
	ds_read_b64_tr_b16 v[162:163], v13 offset:6144
	ds_read_b64_tr_b16 v[182:183], v13 offset:4608
	ds_read_b64_tr_b16 v[184:185], v13 offset:6656
	ds_read_b64_tr_b16 v[198:199], v13 offset:5120
	ds_read_b64_tr_b16 v[200:201], v13 offset:7168
	ds_read_b64_tr_b16 v[202:203], v13 offset:5632
	ds_read_b64_tr_b16 v[204:205], v13 offset:7680
	v_exp_f32_e32 v132, v209
	v_fmamk_f32 v174, v133, 0x3e38aa3b, v207
	v_exp_f32_e32 v133, v174
	s_waitcnt lgkmcnt(8)
	v_fmamk_f32 v208, v134, 0x3e38aa3b, v207
	v_exp_f32_e32 v134, v208
	v_fmamk_f32 v209, v135, 0x3e38aa3b, v207
	v_exp_f32_e32 v135, v209
	v_mfma_f32_32x32x16_bf16 v[64:79], v[96:99], v[80:83], v[64:79]
	v_fmamk_f32 v174, v136, 0x3e38aa3b, v207
	v_exp_f32_e32 v136, v174
	v_fmamk_f32 v208, v137, 0x3e38aa3b, v207
	v_mfma_f32_32x32x16_bf16 v[48:63], v[100:103], v[80:83], v[48:63]
	v_exp_f32_e32 v137, v208
	v_fmamk_f32 v209, v138, 0x3e38aa3b, v207
	v_exp_f32_e32 v138, v209
	v_fmamk_f32 v174, v139, 0x3e38aa3b, v207
	v_mfma_f32_32x32x16_bf16 v[32:47], v[104:107], v[80:83], v[32:47]
	v_exp_f32_e32 v139, v174
	v_fmamk_f32 v208, v140, 0x3e38aa3b, v207
	v_exp_f32_e32 v140, v208
	v_mfma_f32_32x32x16_bf16 v[16:31], v[108:111], v[80:83], v[16:31]
	v_fmamk_f32 v209, v141, 0x3e38aa3b, v207
	v_exp_f32_e32 v141, v209
	v_fmamk_f32 v174, v142, 0x3e38aa3b, v207
	v_exp_f32_e32 v142, v174
	ds_read_b64_tr_b16 v[96:97], v13 offset:8192
	ds_read_b64_tr_b16 v[98:99], v13 offset:10240
	ds_read_b64_tr_b16 v[100:101], v13 offset:8704
	ds_read_b64_tr_b16 v[102:103], v13 offset:10752
	ds_read_b64_tr_b16 v[104:105], v13 offset:9216
	ds_read_b64_tr_b16 v[106:107], v13 offset:11264
	ds_read_b64_tr_b16 v[108:109], v13 offset:9728
	ds_read_b64_tr_b16 v[110:111], v13 offset:11776
	v_fmamk_f32 v208, v143, 0x3e38aa3b, v207
	v_exp_f32_e32 v143, v208
	v_sub_f32_e32 v206, v193, v206
	s_waitcnt lgkmcnt(8)
	v_mul_f32_e32 v206, 0x3e38aa3b, v206
	v_exp_f32_e32 v206, v206
	v_add_f32_e32 v207, 0, v112
	v_cndmask_b32_e64 v194, v206, 1.0, s[0:1]
	v_mfma_f32_32x32x16_bf16 v[64:79], v[160:163], v[84:87], v[64:79]
	v_mov_b32_e32 v193, v14
	v_mov_b32_e32 v174, v113
	v_mov_b32_e32 v208, v114
	v_mov_b32_e32 v209, v115
	v_mfma_f32_32x32x16_bf16 v[48:63], v[182:185], v[84:87], v[48:63]
	v_add_f32_e32 v207, v116, v207
	v_add_f32_e32 v174, v117, v174
	v_add_f32_e32 v208, v118, v208
	v_mfma_f32_32x32x16_bf16 v[32:47], v[198:201], v[84:87], v[32:47]
	v_add_f32_e32 v209, v119, v209
	v_add_f32_e32 v207, v120, v207
	v_add_f32_e32 v174, v121, v174
	v_add_f32_e32 v208, v122, v208
	v_mfma_f32_32x32x16_bf16 v[16:31], v[202:205], v[84:87], v[16:31]
	v_add_f32_e32 v209, v123, v209
	v_add_f32_e32 v207, v124, v207
	v_add_f32_e32 v174, v125, v174
	ds_read_b64_tr_b16 v[160:161], v13 offset:12288
	ds_read_b64_tr_b16 v[162:163], v13 offset:14336
	ds_read_b64_tr_b16 v[182:183], v13 offset:12800
	ds_read_b64_tr_b16 v[184:185], v13 offset:14848
	ds_read_b64_tr_b16 v[198:199], v13 offset:13312
	ds_read_b64_tr_b16 v[200:201], v13 offset:15360
	ds_read_b64_tr_b16 v[202:203], v13 offset:13824
	ds_read_b64_tr_b16 v[204:205], v13 offset:15872
	v_add_f32_e32 v208, v126, v208
	v_add_f32_e32 v209, v127, v209
	v_add_f32_e32 v207, v128, v207
	v_add_f32_e32 v174, v129, v174
	s_waitcnt lgkmcnt(8)
	v_add_f32_e32 v208, v130, v208
	v_add_f32_e32 v209, v131, v209
	v_add_f32_e32 v207, v132, v207
	v_mfma_f32_32x32x16_bf16 v[64:79], v[96:99], v[88:91], v[64:79]
	v_add_f32_e32 v174, v133, v174
	v_add_f32_e32 v208, v134, v208
	v_add_f32_e32 v209, v135, v209
	v_add_f32_e32 v207, v136, v207
	v_mfma_f32_32x32x16_bf16 v[48:63], v[100:103], v[88:91], v[48:63]
	v_add_f32_e32 v174, v137, v174
	v_add_f32_e32 v208, v138, v208
	v_add_f32_e32 v209, v139, v209
	v_add_f32_e32 v207, v140, v207
	v_mfma_f32_32x32x16_bf16 v[32:47], v[104:107], v[88:91], v[32:47]
	v_add_f32_e32 v174, v141, v174
	v_add_f32_e32 v208, v142, v208
	v_add_f32_e32 v207, v207, v174
	v_add_f32_e32 v208, v208, v209
	v_add_f32_e32 v207, v207, v208
	v_add_f32_e32 v15, v143, v207
	v_mfma_f32_32x32x16_bf16 v[16:31], v[108:111], v[88:91], v[16:31]
	v_mov_b32_e32 v195, v15
	v_cvt_pk_bf16_f32 v112, v112, v113
	v_cvt_pk_bf16_f32 v113, v114, v115
	v_cvt_pk_bf16_f32 v114, v116, v117
	s_waitcnt lgkmcnt(0)
	v_cvt_pk_bf16_f32 v115, v118, v119
	v_cvt_pk_bf16_f32 v116, v120, v121
	v_cvt_pk_bf16_f32 v117, v122, v123
	v_mfma_f32_32x32x16_bf16 v[64:79], v[160:163], v[92:95], v[64:79]
	v_cvt_pk_bf16_f32 v118, v124, v125
	v_cvt_pk_bf16_f32 v119, v126, v127
	v_cvt_pk_bf16_f32 v120, v128, v129
	v_cvt_pk_bf16_f32 v121, v130, v131
	v_mfma_f32_32x32x16_bf16 v[48:63], v[182:185], v[92:95], v[48:63]
	v_cvt_pk_bf16_f32 v122, v132, v133
	v_cvt_pk_bf16_f32 v123, v134, v135
	v_cvt_pk_bf16_f32 v124, v136, v137
	v_mfma_f32_32x32x16_bf16 v[32:47], v[198:201], v[92:95], v[32:47]
	v_cvt_pk_bf16_f32 v125, v138, v139
	v_cvt_pk_bf16_f32 v126, v140, v141
	v_cvt_pk_bf16_f32 v127, v142, v143
	s_nop 1
	v_mfma_f32_32x32x16_bf16 v[16:31], v[202:205], v[92:95], v[16:31]
	v_permlane32_swap_b32_e32 v15, v195
	v_permlane32_swap_b32_e32 v112, v114
	v_permlane32_swap_b32_e32 v113, v115
	v_permlane32_swap_b32_e32 v116, v118
	v_permlane32_swap_b32_e32 v117, v119
	v_permlane32_swap_b32_e32 v120, v122
	v_permlane32_swap_b32_e32 v121, v123
	v_permlane32_swap_b32_e32 v124, v126
	v_permlane32_swap_b32_e32 v125, v127
	v_add_f32_e32 v15, v15, v195
	v_fmac_f32_e32 v15, v192, v194
	v_mov_b32_e32 v192, v15
	s_add_i32 s0, s10, 0x8000
	s_and_b32 s0, s0, 0x18000
	v_add_u32_e32 v13, s0, v191
	ds_read_b64_tr_b16 v[128:129], v13 offset:0
	ds_read_b64_tr_b16 v[130:131], v13 offset:2048
	ds_read_b64_tr_b16 v[132:133], v13 offset:512
	ds_read_b64_tr_b16 v[134:135], v13 offset:2560
	ds_read_b64_tr_b16 v[136:137], v13 offset:1024
	ds_read_b64_tr_b16 v[138:139], v13 offset:3072
	ds_read_b64_tr_b16 v[140:141], v13 offset:1536
	ds_read_b64_tr_b16 v[142:143], v13 offset:3584

.Lnl_nors_oa:
	v_max_f32_e32 v206, v113, v113
	v_max_f32_e32 v207, v112, v112
	v_max_f32_e32 v206, v207, v206
	ds_read_b64_tr_b16 v[160:161], v13 offset:4096
	ds_read_b64_tr_b16 v[162:163], v13 offset:6144
	ds_read_b64_tr_b16 v[182:183], v13 offset:4608
	ds_read_b64_tr_b16 v[184:185], v13 offset:6656
	ds_read_b64_tr_b16 v[198:199], v13 offset:5120
	ds_read_b64_tr_b16 v[200:201], v13 offset:7168
	ds_read_b64_tr_b16 v[202:203], v13 offset:5632
	ds_read_b64_tr_b16 v[204:205], v13 offset:7680
	v_max3_f32 v206, v206, v114, v115
	v_max3_f32 v174, v116, v117, v117
	s_waitcnt lgkmcnt(8)
	v_max3_f32 v206, v206, v118, v119
	v_max3_f32 v174, v174, v120, v121
	v_max3_f32 v206, v206, v122, v123
	v_mfma_f32_32x32x16_bf16 v[64:79], v[96:99], v[80:83], v[64:79]
	v_max3_f32 v174, v174, v124, v125
	v_max3_f32 v206, v206, v126, v127
	v_max3_f32 v174, v174, v128, v129
	v_mfma_f32_32x32x16_bf16 v[48:63], v[100:103], v[80:83], v[48:63]
	v_max3_f32 v206, v206, v130, v131
	v_max3_f32 v174, v174, v132, v133
	v_mfma_f32_32x32x16_bf16 v[32:47], v[104:107], v[80:83], v[32:47]
	v_max3_f32 v206, v206, v134, v135
	v_max3_f32 v174, v174, v136, v137
	v_max3_f32 v206, v206, v138, v139
	v_mfma_f32_32x32x16_bf16 v[16:31], v[108:111], v[80:83], v[16:31]
	v_max3_f32 v174, v174, v140, v141
	v_max3_f32 v206, v206, v142, v143
	v_max_f32_e32 v206, v206, v174
	v_mov_b32_e32 v207, v206
	ds_read_b64_tr_b16 v[96:97], v13 offset:8192
	ds_read_b64_tr_b16 v[98:99], v13 offset:10240
	ds_read_b64_tr_b16 v[100:101], v13 offset:8704
	ds_read_b64_tr_b16 v[102:103], v13 offset:10752
	ds_read_b64_tr_b16 v[104:105], v13 offset:9216
	ds_read_b64_tr_b16 v[106:107], v13 offset:11264
	ds_read_b64_tr_b16 v[108:109], v13 offset:9728
	ds_read_b64_tr_b16 v[110:111], v13 offset:11776
	s_nop 1
	v_permlane32_swap_b32_e32 v206, v207
	s_waitcnt lgkmcnt(8)
	v_max_f32_e32 v207, v207, v207
	v_max_f32_e32 v206, v206, v206
	v_max_f32_e32 v206, v206, v207
	v_mfma_f32_32x32x16_bf16 v[64:79], v[160:163], v[84:87], v[64:79]
	v_sub_f32_e32 v207, v206, v193
	v_cmp_ge_f32_e64 s[0:1], s27, v207
	v_max_f32_e32 v206, v206, v206
	v_mfma_f32_32x32x16_bf16 v[48:63], v[182:185], v[84:87], v[48:63]
	v_max_f32_e32 v207, v193, v193
	v_max_f32_e32 v206, v207, v206
	v_mfma_f32_32x32x16_bf16 v[32:47], v[198:201], v[84:87], v[32:47]
	s_cmp_eq_u64 s[0:1], exec
	s_cselect_b64 s[0:1], -1, 0
	v_cndmask_b32_e64 v14, v206, v193, s[0:1]
	v_mul_f32_e32 v207, 0xbe38aa3b, v14
	v_mfma_f32_32x32x16_bf16 v[16:31], v[202:205], v[84:87], v[16:31]
	v_fmamk_f32 v174, v112, 0x3e38aa3b, v207
	v_exp_f32_e32 v112, v174
	v_fmamk_f32 v208, v113, 0x3e38aa3b, v207
	ds_read_b64_tr_b16 v[160:161], v13 offset:12288
	ds_read_b64_tr_b16 v[162:163], v13 offset:14336
	ds_read_b64_tr_b16 v[182:183], v13 offset:12800
	ds_read_b64_tr_b16 v[184:185], v13 offset:14848
	ds_read_b64_tr_b16 v[198:199], v13 offset:13312
	ds_read_b64_tr_b16 v[200:201], v13 offset:15360
	ds_read_b64_tr_b16 v[202:203], v13 offset:13824
	ds_read_b64_tr_b16 v[204:205], v13 offset:15872
	v_exp_f32_e32 v113, v208
	v_fmamk_f32 v209, v114, 0x3e38aa3b, v207
	s_waitcnt lgkmcnt(8)
	v_exp_f32_e32 v114, v209
	v_fmamk_f32 v174, v115, 0x3e38aa3b, v207
	v_exp_f32_e32 v115, v174
	v_mfma_f32_32x32x16_bf16 v[64:79], v[96:99], v[88:91], v[64:79]
	v_fmamk_f32 v208, v116, 0x3e38aa3b, v207
	v_exp_f32_e32 v116, v208
	v_fmamk_f32 v209, v117, 0x3e38aa3b, v207
	v_mfma_f32_32x32x16_bf16 v[48:63], v[100:103], v[88:91], v[48:63]
	v_exp_f32_e32 v117, v209
	v_fmamk_f32 v174, v118, 0x3e38aa3b, v207
	v_exp_f32_e32 v118, v174
	v_mfma_f32_32x32x16_bf16 v[32:47], v[104:107], v[88:91], v[32:47]
	v_fmamk_f32 v208, v119, 0x3e38aa3b, v207
	v_exp_f32_e32 v119, v208
	v_mfma_f32_32x32x16_bf16 v[16:31], v[108:111], v[88:91], v[16:31]
	v_fmamk_f32 v209, v120, 0x3e38aa3b, v207
	v_exp_f32_e32 v120, v209
	v_fmamk_f32 v174, v121, 0x3e38aa3b, v207
	s_waitcnt lgkmcnt(0)
	v_exp_f32_e32 v121, v174
	v_fmamk_f32 v208, v122, 0x3e38aa3b, v207
	v_exp_f32_e32 v122, v208
	v_mfma_f32_32x32x16_bf16 v[64:79], v[160:163], v[92:95], v[64:79]
	v_fmamk_f32 v209, v123, 0x3e38aa3b, v207
	v_exp_f32_e32 v123, v209
	v_mfma_f32_32x32x16_bf16 v[48:63], v[182:185], v[92:95], v[48:63]
	v_fmamk_f32 v174, v124, 0x3e38aa3b, v207
	v_exp_f32_e32 v124, v174
	v_fmamk_f32 v208, v125, 0x3e38aa3b, v207
	v_mfma_f32_32x32x16_bf16 v[32:47], v[198:201], v[92:95], v[32:47]
	v_exp_f32_e32 v125, v208
	v_fmamk_f32 v209, v126, 0x3e38aa3b, v207
	v_exp_f32_e32 v126, v209
	v_mfma_f32_32x32x16_bf16 v[16:31], v[202:205], v[92:95], v[16:31]
	v_fmamk_f32 v174, v127, 0x3e38aa3b, v207
	v_exp_f32_e32 v127, v174
	s_add_i32 s6, s10, 0x10000
	s_and_b32 s6, s6, 0x18000
	v_add_u32_e32 v0, s6, v175
	ds_read_b128 v[2:5], v0 offset:0
	ds_read_b128 v[6:9], v0 offset:8192
	v_add_u32_e32 v0, s6, v176
	ds_read_b128 v[10:13], v0 offset:0
	ds_read_b128 v[160:163], v0 offset:8192
	v_fmamk_f32 v208, v128, 0x3e38aa3b, v207
	v_exp_f32_e32 v128, v208
	v_fmamk_f32 v209, v129, 0x3e38aa3b, v207
	s_waitcnt lgkmcnt(0)
	v_mfma_f32_32x32x16_bf16 v[80:95], v[2:5], v[144:147], 0
	v_exp_f32_e32 v129, v209
	v_fmamk_f32 v174, v130, 0x3e38aa3b, v207
	v_exp_f32_e32 v130, v174
	v_add_u32_e32 v0, s6, v177
	ds_read_b128 v[2:5], v0 offset:0
	v_mfma_f32_32x32x16_bf16 v[96:111], v[6:9], v[144:147], 0
	ds_read_b128 v[6:9], v0 offset:8192
	v_fmamk_f32 v208, v131, 0x3e38aa3b, v207
	v_exp_f32_e32 v131, v208
	v_add_u32_e32 v0, s6, v189
	v_mfma_f32_32x32x16_bf16 v[80:95], v[10:13], v[148:151], v[80:95]
	ds_read_b128 v[10:13], v0 offset:0
	ds_read_b128 v[182:185], v0 offset:8192
	v_fmamk_f32 v209, v132, 0x3e38aa3b, v207
	v_exp_f32_e32 v132, v209
	v_fmamk_f32 v174, v133, 0x3e38aa3b, v207
	s_waitcnt lgkmcnt(0)
	v_mfma_f32_32x32x16_bf16 v[96:111], v[160:163], v[148:151], v[96:111]
	v_exp_f32_e32 v133, v174
	v_fmamk_f32 v208, v134, 0x3e38aa3b, v207
	v_exp_f32_e32 v134, v208
	v_mfma_f32_32x32x16_bf16 v[80:95], v[2:5], v[152:155], v[80:95]
	v_fmamk_f32 v209, v135, 0x3e38aa3b, v207
	v_exp_f32_e32 v135, v209
	v_mfma_f32_32x32x16_bf16 v[96:111], v[6:9], v[152:155], v[96:111]
	v_fmamk_f32 v174, v136, 0x3e38aa3b, v207
	v_exp_f32_e32 v136, v174
	v_fmamk_f32 v208, v137, 0x3e38aa3b, v207
	v_mfma_f32_32x32x16_bf16 v[80:95], v[10:13], v[156:159], v[80:95]
	v_exp_f32_e32 v137, v208
	v_fmamk_f32 v209, v138, 0x3e38aa3b, v207
	v_exp_f32_e32 v138, v209
	v_mfma_f32_32x32x16_bf16 v[96:111], v[182:185], v[156:159], v[96:111]
	v_fmamk_f32 v174, v139, 0x3e38aa3b, v207
	v_exp_f32_e32 v139, v174
	v_fmamk_f32 v208, v140, 0x3e38aa3b, v207
	v_exp_f32_e32 v140, v208
	v_fmamk_f32 v209, v141, 0x3e38aa3b, v207
	v_exp_f32_e32 v141, v209
	v_fmamk_f32 v174, v142, 0x3e38aa3b, v207
	v_exp_f32_e32 v142, v174
	v_fmamk_f32 v208, v143, 0x3e38aa3b, v207
	v_exp_f32_e32 v143, v208
	v_sub_f32_e32 v206, v193, v206
	v_mul_f32_e32 v206, 0x3e38aa3b, v206
	v_exp_f32_e32 v206, v206
	v_add_f32_e32 v207, 0, v112
	v_cndmask_b32_e64 v194, v206, 1.0, s[0:1]
	v_mov_b32_e32 v193, v14
	v_mov_b32_e32 v174, v113
	v_mov_b32_e32 v208, v114
	v_mov_b32_e32 v209, v115
	v_add_f32_e32 v207, v116, v207
	v_add_f32_e32 v174, v117, v174
	v_add_f32_e32 v208, v118, v208
	v_add_f32_e32 v209, v119, v209
	v_add_f32_e32 v207, v120, v207
	v_add_f32_e32 v174, v121, v174
	v_add_f32_e32 v208, v122, v208
	v_add_f32_e32 v209, v123, v209
	v_add_f32_e32 v207, v124, v207
	v_add_f32_e32 v174, v125, v174
	v_add_f32_e32 v208, v126, v208
	v_add_f32_e32 v209, v127, v209
	v_add_f32_e32 v207, v128, v207
	v_add_f32_e32 v174, v129, v174
	v_add_f32_e32 v208, v130, v208
	v_add_f32_e32 v209, v131, v209
	v_add_f32_e32 v207, v132, v207
	v_add_f32_e32 v174, v133, v174
	v_add_f32_e32 v208, v134, v208
	v_add_f32_e32 v209, v135, v209
	v_add_f32_e32 v207, v136, v207
	v_add_f32_e32 v174, v137, v174
	v_add_f32_e32 v208, v138, v208
	v_add_f32_e32 v209, v139, v209
	v_add_f32_e32 v207, v140, v207
	v_add_f32_e32 v174, v141, v174
	v_add_f32_e32 v208, v142, v208
	v_add_f32_e32 v207, v207, v174
	v_add_f32_e32 v208, v208, v209
	v_add_f32_e32 v207, v207, v208
	v_add_f32_e32 v15, v143, v207
	v_mov_b32_e32 v195, v15
	v_cvt_pk_bf16_f32 v112, v112, v113
	v_cvt_pk_bf16_f32 v113, v114, v115
	v_cvt_pk_bf16_f32 v114, v116, v117
	v_cvt_pk_bf16_f32 v115, v118, v119
	v_cvt_pk_bf16_f32 v116, v120, v121
	v_cvt_pk_bf16_f32 v117, v122, v123
	v_cvt_pk_bf16_f32 v118, v124, v125
	v_cvt_pk_bf16_f32 v119, v126, v127
	v_cvt_pk_bf16_f32 v120, v128, v129
	v_cvt_pk_bf16_f32 v121, v130, v131
	v_cvt_pk_bf16_f32 v122, v132, v133
	v_cvt_pk_bf16_f32 v123, v134, v135
	v_cvt_pk_bf16_f32 v124, v136, v137
	v_cvt_pk_bf16_f32 v125, v138, v139
	v_cvt_pk_bf16_f32 v126, v140, v141
	v_cvt_pk_bf16_f32 v127, v142, v143
	s_nop 1
	v_permlane32_swap_b32_e32 v15, v195
	v_permlane32_swap_b32_e32 v112, v114
	v_permlane32_swap_b32_e32 v113, v115
	v_permlane32_swap_b32_e32 v116, v118
	v_permlane32_swap_b32_e32 v117, v119
	v_permlane32_swap_b32_e32 v120, v122
	v_permlane32_swap_b32_e32 v121, v123
	v_permlane32_swap_b32_e32 v124, v126
	v_permlane32_swap_b32_e32 v125, v127
	v_add_f32_e32 v15, v15, v195
	v_fmac_f32_e32 v15, v192, v194
	v_mov_b32_e32 v192, v15
	s_add_i32 s0, s10, 0x8000
	s_and_b32 s0, s0, 0x18000
	v_add_u32_e32 v13, s0, v191
	ds_read_b64_tr_b16 v[128:129], v13 offset:0
	ds_read_b64_tr_b16 v[130:131], v13 offset:2048
	ds_read_b64_tr_b16 v[132:133], v13 offset:512
	ds_read_b64_tr_b16 v[134:135], v13 offset:2560
	ds_read_b64_tr_b16 v[136:137], v13 offset:1024
	ds_read_b64_tr_b16 v[138:139], v13 offset:3072
	ds_read_b64_tr_b16 v[140:141], v13 offset:1536
	ds_read_b64_tr_b16 v[142:143], v13 offset:3584
	s_branch .Lnl_J_o

.Lnl_nors_ob:
	v_max_f32_e32 v206, v113, v113
	v_max_f32_e32 v207, v112, v112
	v_max_f32_e32 v206, v207, v206
	v_max3_f32 v206, v206, v114, v115
	v_max3_f32 v174, v116, v117, v117
	v_max3_f32 v206, v206, v118, v119
	v_max3_f32 v174, v174, v120, v121
	v_max3_f32 v206, v206, v122, v123
	v_max3_f32 v174, v174, v124, v125
	v_max3_f32 v206, v206, v126, v127
	v_max3_f32 v174, v174, v128, v129
	v_max3_f32 v206, v206, v130, v131
	v_max3_f32 v174, v174, v132, v133
	v_max3_f32 v206, v206, v134, v135
	v_max3_f32 v174, v174, v136, v137
	v_max3_f32 v206, v206, v138, v139
	v_max3_f32 v174, v174, v140, v141
	v_max3_f32 v206, v206, v142, v143
	v_max_f32_e32 v206, v206, v174
	v_mov_b32_e32 v207, v206
	s_nop 1
	v_permlane32_swap_b32_e32 v206, v207
	v_max_f32_e32 v207, v207, v207
	v_max_f32_e32 v206, v206, v206
	v_max_f32_e32 v206, v206, v207
	v_sub_f32_e32 v207, v206, v193
	v_cmp_ge_f32_e64 s[0:1], s27, v207
	v_max_f32_e32 v206, v206, v206
	v_max_f32_e32 v207, v193, v193
	v_max_f32_e32 v206, v207, v206
	s_cmp_eq_u64 s[0:1], exec
	s_cselect_b64 s[0:1], -1, 0
	v_cndmask_b32_e64 v14, v206, v193, s[0:1]
	v_mul_f32_e32 v207, 0xbe38aa3b, v14
	v_fmamk_f32 v174, v112, 0x3e38aa3b, v207
	v_exp_f32_e32 v112, v174
	v_fmamk_f32 v208, v113, 0x3e38aa3b, v207
	v_exp_f32_e32 v113, v208
	v_fmamk_f32 v209, v114, 0x3e38aa3b, v207
	v_exp_f32_e32 v114, v209
	v_fmamk_f32 v174, v115, 0x3e38aa3b, v207
	v_exp_f32_e32 v115, v174
	v_fmamk_f32 v208, v116, 0x3e38aa3b, v207
	v_exp_f32_e32 v116, v208
	v_fmamk_f32 v209, v117, 0x3e38aa3b, v207
	v_exp_f32_e32 v117, v209
	v_fmamk_f32 v174, v118, 0x3e38aa3b, v207
	v_exp_f32_e32 v118, v174
	v_fmamk_f32 v208, v119, 0x3e38aa3b, v207
	v_exp_f32_e32 v119, v208
	v_fmamk_f32 v209, v120, 0x3e38aa3b, v207
	v_exp_f32_e32 v120, v209
	v_fmamk_f32 v174, v121, 0x3e38aa3b, v207
	v_exp_f32_e32 v121, v174
	v_fmamk_f32 v208, v122, 0x3e38aa3b, v207
	v_exp_f32_e32 v122, v208
	v_fmamk_f32 v209, v123, 0x3e38aa3b, v207
	v_exp_f32_e32 v123, v209
	v_fmamk_f32 v174, v124, 0x3e38aa3b, v207
	v_exp_f32_e32 v124, v174
	v_fmamk_f32 v208, v125, 0x3e38aa3b, v207
	v_exp_f32_e32 v125, v208
	v_fmamk_f32 v209, v126, 0x3e38aa3b, v207
	v_exp_f32_e32 v126, v209
	v_fmamk_f32 v174, v127, 0x3e38aa3b, v207
	v_exp_f32_e32 v127, v174
	v_fmamk_f32 v208, v128, 0x3e38aa3b, v207
	v_exp_f32_e32 v128, v208
	v_fmamk_f32 v209, v129, 0x3e38aa3b, v207
	v_exp_f32_e32 v129, v209
	v_fmamk_f32 v174, v130, 0x3e38aa3b, v207
	v_exp_f32_e32 v130, v174
	v_fmamk_f32 v208, v131, 0x3e38aa3b, v207
	v_exp_f32_e32 v131, v208
	v_fmamk_f32 v209, v132, 0x3e38aa3b, v207
	ds_read_b64_tr_b16 v[160:161], v13 offset:4096
	ds_read_b64_tr_b16 v[162:163], v13 offset:6144
	ds_read_b64_tr_b16 v[182:183], v13 offset:4608
	ds_read_b64_tr_b16 v[184:185], v13 offset:6656
	ds_read_b64_tr_b16 v[198:199], v13 offset:5120
	ds_read_b64_tr_b16 v[200:201], v13 offset:7168
	ds_read_b64_tr_b16 v[202:203], v13 offset:5632
	ds_read_b64_tr_b16 v[204:205], v13 offset:7680
	v_exp_f32_e32 v132, v209
	v_fmamk_f32 v174, v133, 0x3e38aa3b, v207
	s_waitcnt lgkmcnt(8)
	v_exp_f32_e32 v133, v174
	v_fmamk_f32 v208, v134, 0x3e38aa3b, v207
	v_exp_f32_e32 v134, v208
	v_mfma_f32_32x32x16_bf16 v[64:79], v[96:99], v[80:83], v[64:79]
	v_fmamk_f32 v209, v135, 0x3e38aa3b, v207
	v_exp_f32_e32 v135, v209
	v_mfma_f32_32x32x16_bf16 v[48:63], v[100:103], v[80:83], v[48:63]
	v_fmamk_f32 v174, v136, 0x3e38aa3b, v207
	v_exp_f32_e32 v136, v174
	v_fmamk_f32 v208, v137, 0x3e38aa3b, v207
	v_mfma_f32_32x32x16_bf16 v[32:47], v[104:107], v[80:83], v[32:47]
	v_exp_f32_e32 v137, v208
	v_fmamk_f32 v209, v138, 0x3e38aa3b, v207
	v_mfma_f32_32x32x16_bf16 v[16:31], v[108:111], v[80:83], v[16:31]
	v_exp_f32_e32 v138, v209
	v_fmamk_f32 v174, v139, 0x3e38aa3b, v207
	v_exp_f32_e32 v139, v174
	ds_read_b64_tr_b16 v[96:97], v13 offset:8192
	ds_read_b64_tr_b16 v[98:99], v13 offset:10240
	ds_read_b64_tr_b16 v[100:101], v13 offset:8704
	ds_read_b64_tr_b16 v[102:103], v13 offset:10752
	ds_read_b64_tr_b16 v[104:105], v13 offset:9216
	ds_read_b64_tr_b16 v[106:107], v13 offset:11264
	ds_read_b64_tr_b16 v[108:109], v13 offset:9728
	ds_read_b64_tr_b16 v[110:111], v13 offset:11776
	v_fmamk_f32 v208, v140, 0x3e38aa3b, v207
	v_exp_f32_e32 v140, v208
	s_waitcnt lgkmcnt(8)
	v_fmamk_f32 v209, v141, 0x3e38aa3b, v207
	v_exp_f32_e32 v141, v209
	v_fmamk_f32 v174, v142, 0x3e38aa3b, v207
	v_mfma_f32_32x32x16_bf16 v[64:79], v[160:163], v[84:87], v[64:79]
	v_exp_f32_e32 v142, v174
	v_fmamk_f32 v208, v143, 0x3e38aa3b, v207
	v_exp_f32_e32 v143, v208
	v_mfma_f32_32x32x16_bf16 v[48:63], v[182:185], v[84:87], v[48:63]
	v_sub_f32_e32 v206, v193, v206
	v_mul_f32_e32 v206, 0x3e38aa3b, v206
	v_mfma_f32_32x32x16_bf16 v[32:47], v[198:201], v[84:87], v[32:47]
	v_exp_f32_e32 v206, v206
	v_add_f32_e32 v207, 0, v112
	v_cndmask_b32_e64 v194, v206, 1.0, s[0:1]
	v_mfma_f32_32x32x16_bf16 v[16:31], v[202:205], v[84:87], v[16:31]
	v_mov_b32_e32 v193, v14
	v_mov_b32_e32 v174, v113
	ds_read_b64_tr_b16 v[160:161], v13 offset:12288
	ds_read_b64_tr_b16 v[162:163], v13 offset:14336
	ds_read_b64_tr_b16 v[182:183], v13 offset:12800
	ds_read_b64_tr_b16 v[184:185], v13 offset:14848
	ds_read_b64_tr_b16 v[198:199], v13 offset:13312
	ds_read_b64_tr_b16 v[200:201], v13 offset:15360
	ds_read_b64_tr_b16 v[202:203], v13 offset:13824
	ds_read_b64_tr_b16 v[204:205], v13 offset:15872
	v_mov_b32_e32 v208, v114
	v_mov_b32_e32 v209, v115
	v_add_f32_e32 v207, v116, v207
	s_waitcnt lgkmcnt(8)
	v_add_f32_e32 v174, v117, v174
	v_add_f32_e32 v208, v118, v208
	v_mfma_f32_32x32x16_bf16 v[64:79], v[96:99], v[88:91], v[64:79]
	v_add_f32_e32 v209, v119, v209
	v_add_f32_e32 v207, v120, v207
	v_add_f32_e32 v174, v121, v174
	v_mfma_f32_32x32x16_bf16 v[48:63], v[100:103], v[88:91], v[48:63]
	v_add_f32_e32 v208, v122, v208
	v_add_f32_e32 v209, v123, v209
	v_add_f32_e32 v207, v124, v207
	v_mfma_f32_32x32x16_bf16 v[32:47], v[104:107], v[88:91], v[32:47]
	v_add_f32_e32 v174, v125, v174
	v_add_f32_e32 v208, v126, v208
	v_mfma_f32_32x32x16_bf16 v[16:31], v[108:111], v[88:91], v[16:31]
	v_add_f32_e32 v209, v127, v209
	v_add_f32_e32 v207, v128, v207
	v_add_f32_e32 v174, v129, v174
	s_waitcnt lgkmcnt(0)
	v_add_f32_e32 v208, v130, v208
	v_add_f32_e32 v209, v131, v209
	v_mfma_f32_32x32x16_bf16 v[64:79], v[160:163], v[92:95], v[64:79]
	v_add_f32_e32 v207, v132, v207
	v_add_f32_e32 v174, v133, v174
	v_add_f32_e32 v208, v134, v208
	v_mfma_f32_32x32x16_bf16 v[48:63], v[182:185], v[92:95], v[48:63]
	v_add_f32_e32 v209, v135, v209
	v_add_f32_e32 v207, v136, v207
	v_mfma_f32_32x32x16_bf16 v[32:47], v[198:201], v[92:95], v[32:47]
	v_add_f32_e32 v174, v137, v174
	v_add_f32_e32 v208, v138, v208
	v_add_f32_e32 v209, v139, v209
	v_mfma_f32_32x32x16_bf16 v[16:31], v[202:205], v[92:95], v[16:31]
	v_add_f32_e32 v207, v140, v207
	v_add_f32_e32 v174, v141, v174
	s_add_i32 s6, s10, 0x10000
	s_and_b32 s6, s6, 0x18000
	v_add_u32_e32 v0, s6, v175
	ds_read_b128 v[2:5], v0 offset:0
	ds_read_b128 v[6:9], v0 offset:8192
	v_add_u32_e32 v0, s6, v176
	ds_read_b128 v[10:13], v0 offset:0
	ds_read_b128 v[160:163], v0 offset:8192
	v_add_f32_e32 v208, v142, v208
	v_add_f32_e32 v207, v207, v174
	v_add_f32_e32 v208, v208, v209
	v_add_f32_e32 v207, v207, v208
	v_add_f32_e32 v15, v143, v207
	v_mov_b32_e32 v195, v15
	s_waitcnt lgkmcnt(0)
	v_mfma_f32_32x32x16_bf16 v[80:95], v[2:5], v[144:147], 0
	v_cvt_pk_bf16_f32 v112, v112, v113
	v_cvt_pk_bf16_f32 v113, v114, v115
	v_cvt_pk_bf16_f32 v114, v116, v117
	v_add_u32_e32 v0, s6, v177
	ds_read_b128 v[2:5], v0 offset:0
	v_mfma_f32_32x32x16_bf16 v[96:111], v[6:9], v[144:147], 0
	ds_read_b128 v[6:9], v0 offset:8192
	v_cvt_pk_bf16_f32 v115, v118, v119
	v_cvt_pk_bf16_f32 v116, v120, v121
	v_add_u32_e32 v0, s6, v189
	v_mfma_f32_32x32x16_bf16 v[80:95], v[10:13], v[148:151], v[80:95]
	ds_read_b128 v[10:13], v0 offset:0
	ds_read_b128 v[182:185], v0 offset:8192
	v_cvt_pk_bf16_f32 v117, v122, v123
	v_cvt_pk_bf16_f32 v118, v124, v125
	v_cvt_pk_bf16_f32 v119, v126, v127
	s_waitcnt lgkmcnt(0)
	v_mfma_f32_32x32x16_bf16 v[96:111], v[160:163], v[148:151], v[96:111]
	v_cvt_pk_bf16_f32 v120, v128, v129
	v_cvt_pk_bf16_f32 v121, v130, v131
	v_mfma_f32_32x32x16_bf16 v[80:95], v[2:5], v[152:155], v[80:95]
	v_cvt_pk_bf16_f32 v122, v132, v133
	v_cvt_pk_bf16_f32 v123, v134, v135
	v_cvt_pk_bf16_f32 v124, v136, v137
	v_mfma_f32_32x32x16_bf16 v[96:111], v[6:9], v[152:155], v[96:111]
	v_cvt_pk_bf16_f32 v125, v138, v139
	v_cvt_pk_bf16_f32 v126, v140, v141
	v_mfma_f32_32x32x16_bf16 v[80:95], v[10:13], v[156:159], v[80:95]
	v_cvt_pk_bf16_f32 v127, v142, v143
	s_nop 1
	v_permlane32_swap_b32_e32 v15, v195
	v_mfma_f32_32x32x16_bf16 v[96:111], v[182:185], v[156:159], v[96:111]
	v_permlane32_swap_b32_e32 v112, v114
	v_permlane32_swap_b32_e32 v113, v115
	v_permlane32_swap_b32_e32 v116, v118
	v_permlane32_swap_b32_e32 v117, v119
	v_permlane32_swap_b32_e32 v120, v122
	v_permlane32_swap_b32_e32 v121, v123
	v_permlane32_swap_b32_e32 v124, v126
	v_permlane32_swap_b32_e32 v125, v127
	v_add_f32_e32 v15, v15, v195
	v_fmac_f32_e32 v15, v192, v194
	v_mov_b32_e32 v192, v15
	s_add_i32 s0, s10, 0x8000
	s_and_b32 s0, s0, 0x18000
	v_add_u32_e32 v13, s0, v191
	ds_read_b64_tr_b16 v[128:129], v13 offset:0
	ds_read_b64_tr_b16 v[130:131], v13 offset:2048
	ds_read_b64_tr_b16 v[132:133], v13 offset:512
	ds_read_b64_tr_b16 v[134:135], v13 offset:2560
	ds_read_b64_tr_b16 v[136:137], v13 offset:1024
	ds_read_b64_tr_b16 v[138:139], v13 offset:3072
	ds_read_b64_tr_b16 v[140:141], v13 offset:1536
	ds_read_b64_tr_b16 v[142:143], v13 offset:3584
